# baseline (speedup 1.0000x reference)
.LBB0_635:
	s_bfe_u32 s15, s14, 0x10006
	s_bfe_i32 s6, s14, 0x10006
	s_and_b32 s16, s14, 63
	s_lshl_b32 s0, s15, 25
	s_add_u32 s0, s38, s0
	s_addc_u32 s1, s39, 0
	s_add_u32 s12, s0, 0x17a00000
	s_addc_u32 s13, s1, 0
	s_lshl_b32 s0, s15, 12
	v_readlane_b32 s1, v253, 32
	s_add_u32 s4, s1, s0
	v_readlane_b32 s0, v253, 33
	s_addc_u32 s5, s0, 0
	s_and_b32 s2, s14, 0xffffff80
	s_ashr_i32 s3, s2, 31
	s_lshl_b64 s[0:1], s[2:3], 2
	s_add_u32 s0, s4, s0
	s_addc_u32 s1, s5, s1
	s_lshl_b32 s7, s16, 8
	s_xor_b32 s9, s7, 0x3f00
	s_cmp_eq_u32 s15, 0
	v_mov_b32_e32 v70, v212
	s_cselect_b64 vcc, -1, 0
	s_and_b64 s[4:5], vcc, exec
	v_ashrrev_i32_e32 v74, 7, v70
	v_lshlrev_b32_e32 v7, 4, v74
	s_cselect_b32 s18, s7, s9
	s_and_b32 s4, s6, 0xc0
	v_sub_u32_e32 v0, 63, v7
	s_or_b32 s4, s18, s4
	v_ashrrev_i32_e32 v75, 4, v70
	v_cndmask_b32_e32 v8, v0, v7, vcc
	v_lshlrev_b32_e32 v0, 3, v70
	v_add_u32_e32 v2, s4, v75
	v_and_b32_e32 v9, 0x78, v0
	v_ashrrev_i32_e32 v3, 31, v2
	v_or_b32_e32 v66, s2, v9
	v_mov_b32_e32 v67, s3
	v_lshlrev_b64 v[2:3], 10, v[2:3]
	v_lshl_add_u64 v[2:3], v[2:3], 0, v[66:67]
	v_lshlrev_b64 v[2:3], 1, v[2:3]
	v_add_u32_e32 v10, 0x200, v70
	v_lshl_add_u64 v[4:5], s[12:13], 0, v[2:3]
	v_lshl_add_u64 v[2:3], s[76:77], 0, v[2:3]
	v_ashrrev_i32_e32 v76, 4, v10
	global_load_dwordx4 v[34:37], v[4:5], off
	global_load_dwordx4 v[38:41], v[2:3], off
	v_add_u32_e32 v2, s4, v76
	v_ashrrev_i32_e32 v3, 31, v2
	v_lshlrev_b64 v[2:3], 10, v[2:3]
	v_lshl_add_u64 v[2:3], v[2:3], 0, v[66:67]
	v_lshlrev_b64 v[2:3], 1, v[2:3]
	v_lshl_add_u64 v[4:5], s[12:13], 0, v[2:3]
	v_lshl_add_u64 v[2:3], s[76:77], 0, v[2:3]
	global_load_dwordx4 v[42:45], v[4:5], off
	global_load_dwordx4 v[46:49], v[2:3], off
	v_lshlrev_b32_e32 v0, 2, v9
	v_lshl_add_u64 v[68:69], s[0:1], 0, v[0:1]
	global_load_dwordx4 v[236:239], v[68:69], off
	global_load_dwordx4 v[240:243], v[68:69], off offset:16
	s_add_i32 s0, 0, 0x1a000
	v_lshlrev_b32_e32 v12, 5, v70
	v_add_u32_e32 v2, s0, v0
	v_and_b32_e32 v12, 0xfffffe00, v12
	v_add_u32_e32 v80, v2, v12
	v_or_b32_e32 v12, 1, v7
	v_sub_u32_e32 v13, 63, v12
	v_cndmask_b32_e32 v12, v13, v12, vcc
	v_or_b32_e32 v13, 2, v7
	v_sub_u32_e32 v14, 63, v13
	v_cndmask_b32_e32 v13, v14, v13, vcc
	v_or_b32_e32 v14, 3, v7
	v_sub_u32_e32 v15, 63, v14
	v_cndmask_b32_e32 v14, v15, v14, vcc
	v_or_b32_e32 v15, 4, v7
	v_sub_u32_e32 v16, 63, v15
	v_cndmask_b32_e32 v15, v16, v15, vcc
	v_or_b32_e32 v16, 5, v7
	v_sub_u32_e32 v17, 63, v16
	v_cndmask_b32_e32 v16, v17, v16, vcc
	v_or_b32_e32 v17, 6, v7
	v_sub_u32_e32 v18, 63, v17
	v_cndmask_b32_e32 v17, v18, v17, vcc
	v_or_b32_e32 v18, 7, v7
	v_sub_u32_e32 v19, 63, v18
	v_cndmask_b32_e32 v18, v19, v18, vcc
	v_or_b32_e32 v19, 8, v7
	v_sub_u32_e32 v20, 63, v19
	v_cndmask_b32_e32 v19, v20, v19, vcc
	v_or_b32_e32 v20, 9, v7
	v_sub_u32_e32 v21, 63, v20
	v_cndmask_b32_e32 v20, v21, v20, vcc
	v_or_b32_e32 v21, 10, v7
	v_sub_u32_e32 v22, 63, v21
	v_cndmask_b32_e32 v21, v22, v21, vcc
	v_or_b32_e32 v22, 11, v7
	v_sub_u32_e32 v23, 63, v22
	v_cndmask_b32_e32 v22, v23, v22, vcc
	v_or_b32_e32 v23, 12, v7
	v_lshrrev_b32_e32 v27, 7, v70
	v_lshrrev_b32_e32 v10, 7, v10
	v_sub_u32_e32 v24, 63, v23
	v_xor_b32_e32 v27, v27, v70
	v_xor_b32_e32 v10, v10, v70
	v_readfirstlane_b32 s8, v70
	v_cndmask_b32_e32 v23, v24, v23, vcc
	v_or_b32_e32 v24, 13, v7
	v_lshlrev_b32_e32 v27, 4, v27
	v_lshlrev_b32_e32 v28, 1, v75
	v_lshlrev_b32_e32 v10, 4, v10
	v_lshlrev_b32_e32 v29, 1, v76
	v_and_b32_e32 v71, 31, v70
	s_and_b32 s42, s8, 64
	v_sub_u32_e32 v25, 63, v24
	v_and_b32_e32 v27, 0x70, v27
	v_and_b32_e32 v28, 14, v28
	v_mul_u32_u24_e32 v9, 0x90, v9
	v_and_b32_e32 v10, 0x70, v10
	v_and_b32_e32 v29, 14, v29
	s_ashr_i32 s17, s8, 7
	s_movk_i32 s1, 0x90
	v_cndmask_b32_e32 v24, v25, v24, vcc
	v_or_b32_e32 v25, 14, v7
	v_or3_b32 v27, v27, v28, v9
	v_or3_b32 v9, v10, v29, v9
	v_or_b32_e32 v10, s42, v71
	v_bfe_u32 v72, v70, 5, 1
	v_and_b32_e32 v3, 0x7f, v70
	v_lshl_or_b32 v5, s17, 5, v71
	v_sub_u32_e32 v26, 63, v25
	v_or_b32_e32 v7, 15, v7
	v_mad_u32_u24 v29, v10, s1, 0
	v_or_b32_e32 v10, 32, v10
	v_lshrrev_b32_e32 v6, 5, v70
	v_lshlrev_b32_e32 v73, 2, v3
	v_mul_lo_u32 v11, v5, s1
	v_lshrrev_b32_e32 v5, 3, v5
	v_cndmask_b32_e32 v25, v26, v25, vcc
	v_sub_u32_e32 v26, 63, v7
	v_bfe_u32 v30, v70, 3, 2
	v_or_b32_e32 v32, 2, v72
	v_or_b32_e32 v51, 4, v72
	v_or_b32_e32 v54, 6, v72
	v_mad_u32_u24 v55, v10, s1, 0
	v_lshrrev_b32_e32 v10, 3, v10
	v_add_u32_e32 v3, s0, v73
	s_and_b32 s0, s8, 0xffffff80
	v_readlane_b32 s8, v255, 4
	v_cndmask_b32_e32 v7, v26, v7, vcc
	v_bitop3_b32 v31, v5, v72, 7 bitop3:0x6c
	v_bitop3_b32 v6, v6, v30, 1 bitop3:0x6c
	v_bitop3_b32 v33, v5, v32, 7 bitop3:0x6c
	v_bitop3_b32 v50, v72, v30, 2 bitop3:0x36
	v_bitop3_b32 v52, v5, v51, 7 bitop3:0x6c
	v_bitop3_b32 v53, v72, v30, 4 bitop3:0x36
	v_bitop3_b32 v5, v5, v54, 7 bitop3:0x6c
	v_bitop3_b32 v30, v72, v30, 6 bitop3:0x36
	v_bitop3_b32 v56, v10, v72, 7 bitop3:0x6c
	v_bitop3_b32 v32, v10, v32, 7 bitop3:0x6c
	v_bitop3_b32 v51, v10, v51, 7 bitop3:0x6c
	v_bitop3_b32 v10, v10, v54, 7 bitop3:0x6c
	v_readlane_b32 s2, v255, 2
	v_readlane_b32 s3, v255, 3
	s_add_i32 s0, s8, s0
	v_lshlrev_b32_e32 v4, 4, v72
	v_add_u32_e32 v11, 0, v11
	v_lshlrev_b32_e32 v8, 9, v8
	v_lshlrev_b32_e32 v12, 9, v12
	v_lshlrev_b32_e32 v13, 9, v13
	v_lshlrev_b32_e32 v14, 9, v14
	v_lshlrev_b32_e32 v15, 9, v15
	v_lshlrev_b32_e32 v16, 9, v16
	v_lshlrev_b32_e32 v17, 9, v17
	v_lshlrev_b32_e32 v18, 9, v18
	v_lshlrev_b32_e32 v19, 9, v19
	v_lshlrev_b32_e32 v20, 9, v20
	v_lshlrev_b32_e32 v21, 9, v21
	v_lshlrev_b32_e32 v22, 9, v22
	v_lshlrev_b32_e32 v23, 9, v23
	v_lshlrev_b32_e32 v24, 9, v24
	v_lshlrev_b32_e32 v25, 9, v25
	v_lshlrev_b32_e32 v7, 9, v7
	v_lshlrev_b32_e32 v26, 9, v75
	v_lshlrev_b32_e32 v28, 9, v76
	v_lshlrev_b32_e32 v31, 4, v31
	v_lshlrev_b32_e32 v6, 4, v6
	v_lshlrev_b32_e32 v33, 4, v33
	v_lshlrev_b32_e32 v50, 4, v50
	v_lshlrev_b32_e32 v52, 4, v52
	v_lshlrev_b32_e32 v53, 4, v53
	v_lshlrev_b32_e32 v5, 4, v5
	v_lshlrev_b32_e32 v30, 4, v30
	v_lshlrev_b32_e32 v56, 4, v56
	v_lshlrev_b32_e32 v32, 4, v32
	v_lshlrev_b32_e32 v51, 4, v51
	v_lshlrev_b32_e32 v10, 4, v10
	v_mov_b32_e32 v81, 0
	s_mov_b32 s19, 0
	v_lshl_add_u32 v77, v70, 2, s2
	v_cmp_lt_i32_e64 s[6:7], 0, v74
	v_cmp_eq_u32_e64 s[4:5], 3, v74
	v_add_u32_e32 v0, s3, v0
	v_add_u32_e32 v78, s8, v73
	v_add_u32_e32 v79, s3, v73
	v_add_u32_e32 v82, s2, v73
	v_add_u32_e32 v83, v2, v26
	v_add_u32_e32 v84, 0, v27
	v_add_u32_e32 v85, v2, v28
	v_add_u32_e32 v86, 0, v9
	v_add_u32_e32 v87, v11, v31
	v_add_u32_e32 v88, v29, v6
	v_add_u32_e32 v89, v11, v33
	v_add_u32_e32 v90, v29, v50
	v_add_u32_e32 v91, v11, v52
	v_add_u32_e32 v92, v29, v53
	v_add_u32_e32 v93, v11, v5
	v_add_u32_e32 v94, v29, v30
	v_add_u32_e32 v95, s0, v4
	v_add_u32_e32 v96, v55, v56
	v_add_u32_e32 v97, v55, v32
	v_add_u32_e32 v98, v55, v51
	v_add_u32_e32 v99, v55, v10
	v_add_u32_e32 v100, v3, v8
	v_add_u32_e32 v101, v3, v12
	v_add_u32_e32 v102, v3, v13
	v_add_u32_e32 v103, v3, v14
	v_add_u32_e32 v104, v3, v15
	v_add_u32_e32 v105, v3, v16
	v_add_u32_e32 v106, v3, v17
	v_add_u32_e32 v107, v3, v18
	v_add_u32_e32 v108, v3, v19
	v_add_u32_e32 v109, v3, v20
	v_add_u32_e32 v110, v3, v21
	v_add_u32_e32 v111, v3, v22
	v_add_u32_e32 v112, v3, v23
	v_add_u32_e32 v113, v3, v24
	v_add_u32_e32 v114, v3, v25
	v_add_u32_e32 v115, v3, v7
	v_mov_b32_e32 v18, 0
	v_mov_b32_e32 v19, v81
	v_mov_b32_e32 v20, v81
	v_mov_b32_e32 v21, v81
	v_mov_b32_e32 v22, v81
	v_mov_b32_e32 v23, v81
	v_mov_b32_e32 v24, v81
	v_mov_b32_e32 v25, v81
	v_mov_b32_e32 v26, v81
	v_mov_b32_e32 v27, v81
	v_mov_b32_e32 v28, v81
	v_mov_b32_e32 v29, v81
	v_mov_b32_e32 v30, v81
	v_mov_b32_e32 v31, v81
	v_mov_b32_e32 v32, v81
	v_mov_b32_e32 v33, v81
	v_mov_b32_e32 v2, 0
	v_mov_b32_e32 v3, v81
	v_mov_b32_e32 v4, v81
	v_mov_b32_e32 v5, v81
	v_mov_b32_e32 v6, v81
	v_mov_b32_e32 v7, v81
	v_mov_b32_e32 v8, v81
	v_mov_b32_e32 v9, v81
	v_mov_b32_e32 v10, v81
	v_mov_b32_e32 v11, v81
	v_mov_b32_e32 v12, v81
	v_mov_b32_e32 v13, v81
	v_mov_b32_e32 v14, v81
	v_mov_b32_e32 v15, v81
	v_mov_b32_e32 v16, v81
	v_mov_b32_e32 v17, v81
.LBB0_636:
	s_waitcnt vmcnt(0)
	v_mov_b64_e32 v[50:51], v[236:237]
	v_mov_b64_e32 v[52:53], v[238:239]
	v_lshlrev_b32_e32 v54, 16, v34
	v_mul_f32_e32 v54, 0xbfb8aa3b, v54
	v_exp_f32_e32 v54, v54
	v_lshlrev_b32_e32 v62, 16, v36
	v_mul_f32_e32 v62, 0xbfb8aa3b, v62
	v_exp_f32_e32 v62, v62
	v_add_f32_e32 v54, 1.0, v54
	v_rcp_f32_e32 v54, v54
	v_add_f32_e32 v62, 1.0, v62
	v_rcp_f32_e32 v62, v62
	v_sub_f32_e32 v124, 1.0, v50
	v_fma_f32 v116, v54, v124, v50
	v_cmp_gt_f32_e64 s[8:9], s63, v116
	v_sub_f32_e32 v123, 1.0, v51
	v_sub_f32_e32 v122, 1.0, v52
	v_cndmask_b32_e64 v54, 0, 32, s[8:9]
	v_ldexp_f32 v54, v116, v54
	v_log_f32_e32 v54, v54
	v_sub_f32_e32 v121, 1.0, v53
	v_mul_f32_e32 v55, 0x3f317217, v54
	v_fma_f32 v55, v54, s61, -v55
	v_fmac_f32_e32 v55, 0x3377d1cf, v54
	v_fmac_f32_e32 v55, 0x3f317217, v54
	v_cmp_lt_f32_e64 s[10:11], |v54|, s55
	s_nop 1
	v_cndmask_b32_e64 v54, v54, v55, s[10:11]
	v_cndmask_b32_e64 v55, 0, v216, s[8:9]
	v_sub_f32_e32 v58, v54, v55
	v_and_b32_e32 v54, 0xffff0000, v34
	v_mul_f32_e32 v54, 0xbfb8aa3b, v54
	v_exp_f32_e32 v54, v54
	s_nop 0
	v_add_f32_e32 v54, 1.0, v54
	v_rcp_f32_e32 v54, v54
	s_nop 0
	v_fma_f32 v117, v54, v123, v51
	v_cmp_gt_f32_e64 s[8:9], s63, v117
	s_nop 1
	v_cndmask_b32_e64 v54, 0, 32, s[8:9]
	v_ldexp_f32 v54, v117, v54
	v_log_f32_e32 v54, v54
	s_nop 0
	v_mul_f32_e32 v55, 0x3f317217, v54
	v_fma_f32 v55, v54, s61, -v55
	v_fmac_f32_e32 v55, 0x3377d1cf, v54
	v_fmac_f32_e32 v55, 0x3f317217, v54
	v_cmp_lt_f32_e64 s[10:11], |v54|, s55
	s_nop 1
	v_cndmask_b32_e64 v54, v54, v55, s[10:11]
	v_cndmask_b32_e64 v55, 0, v216, s[8:9]
	v_sub_f32_e32 v59, v54, v55
	v_lshlrev_b32_e32 v54, 16, v35
	v_mul_f32_e32 v54, 0xbfb8aa3b, v54
	v_exp_f32_e32 v54, v54
	s_nop 0
	v_add_f32_e32 v54, 1.0, v54
	v_rcp_f32_e32 v54, v54
	s_nop 0
	v_fma_f32 v118, v54, v122, v52
	v_cmp_gt_f32_e64 s[8:9], s63, v118
	s_nop 1
	v_cndmask_b32_e64 v54, 0, 32, s[8:9]
	v_ldexp_f32 v54, v118, v54
	v_log_f32_e32 v54, v54
	s_nop 0
	v_mul_f32_e32 v55, 0x3f317217, v54
	v_fma_f32 v55, v54, s61, -v55
	v_fmac_f32_e32 v55, 0x3377d1cf, v54
	v_fmac_f32_e32 v55, 0x3f317217, v54
	v_cmp_lt_f32_e64 s[10:11], |v54|, s55
	s_nop 1
	v_cndmask_b32_e64 v54, v54, v55, s[10:11]
	v_cndmask_b32_e64 v55, 0, v216, s[8:9]
	v_sub_f32_e32 v60, v54, v55
	v_and_b32_e32 v54, 0xffff0000, v35
	v_mul_f32_e32 v54, 0xbfb8aa3b, v54
	v_exp_f32_e32 v54, v54
	s_nop 0
	v_add_f32_e32 v54, 1.0, v54
	v_rcp_f32_e32 v54, v54
	s_nop 0
	v_fma_f32 v119, v54, v121, v53
	v_cmp_gt_f32_e64 s[8:9], s63, v119
	s_nop 1
	v_cndmask_b32_e64 v54, 0, 32, s[8:9]
	v_ldexp_f32 v54, v119, v54
	v_log_f32_e32 v54, v54
	s_nop 0
	v_mul_f32_e32 v55, 0x3f317217, v54
	v_fma_f32 v55, v54, s61, -v55
	v_fmac_f32_e32 v55, 0x3377d1cf, v54
	v_fmac_f32_e32 v55, 0x3f317217, v54
	v_cmp_lt_f32_e64 s[10:11], |v54|, s55
	s_nop 1
	v_cndmask_b32_e64 v54, v54, v55, s[10:11]
	v_cndmask_b32_e64 v55, 0, v216, s[8:9]
	v_sub_f32_e32 v61, v54, v55
	s_waitcnt vmcnt(0)
	v_mov_b64_e32 v[54:55], v[240:241]
	v_mov_b64_e32 v[56:57], v[242:243]
	v_sub_f32_e32 v125, 1.0, v54
	v_fma_f32 v120, v62, v125, v54
	v_cmp_gt_f32_e64 s[8:9], s63, v120
	v_sub_f32_e32 v127, 1.0, v55
	v_sub_f32_e32 v130, 1.0, v56
	v_cndmask_b32_e64 v62, 0, 32, s[8:9]
	v_ldexp_f32 v62, v120, v62
	v_log_f32_e32 v62, v62
	v_sub_f32_e32 v131, 1.0, v57
	v_mul_f32_e32 v63, 0x3f317217, v62
	v_fma_f32 v63, v62, s61, -v63
	v_fmac_f32_e32 v63, 0x3377d1cf, v62
	v_fmac_f32_e32 v63, 0x3f317217, v62
	v_cmp_lt_f32_e64 s[10:11], |v62|, s55
	s_nop 1
	v_cndmask_b32_e64 v62, v62, v63, s[10:11]
	v_cndmask_b32_e64 v63, 0, v216, s[8:9]
	v_sub_f32_e32 v62, v62, v63
	v_and_b32_e32 v63, 0xffff0000, v36
	v_mul_f32_e32 v63, 0xbfb8aa3b, v63
	v_exp_f32_e32 v63, v63
	s_nop 0
	v_add_f32_e32 v63, 1.0, v63
	v_rcp_f32_e32 v63, v63
	s_nop 0
	v_fma_f32 v126, v63, v127, v55
	v_cmp_gt_f32_e64 s[8:9], s63, v126
	s_nop 1
	v_cndmask_b32_e64 v63, 0, 32, s[8:9]
	v_ldexp_f32 v63, v126, v63
	v_log_f32_e32 v63, v63
	s_nop 0
	v_mul_f32_e32 v64, 0x3f317217, v63
	v_fma_f32 v64, v63, s61, -v64
	v_fmac_f32_e32 v64, 0x3377d1cf, v63
	v_fmac_f32_e32 v64, 0x3f317217, v63
	v_cmp_lt_f32_e64 s[10:11], |v63|, s55
	s_nop 1
	v_cndmask_b32_e64 v63, v63, v64, s[10:11]
	v_cndmask_b32_e64 v64, 0, v216, s[8:9]
	v_sub_f32_e32 v63, v63, v64
	v_lshlrev_b32_e32 v64, 16, v37
	v_mul_f32_e32 v64, 0xbfb8aa3b, v64
	v_exp_f32_e32 v64, v64
	s_nop 0
	v_add_f32_e32 v64, 1.0, v64
	v_rcp_f32_e32 v64, v64
	s_nop 0
	v_fma_f32 v128, v64, v130, v56
	v_cmp_gt_f32_e64 s[8:9], s63, v128
	s_nop 1
	v_cndmask_b32_e64 v64, 0, 32, s[8:9]
	v_ldexp_f32 v64, v128, v64
	v_log_f32_e32 v64, v64
	s_nop 0
	v_mul_f32_e32 v65, 0x3f317217, v64
	v_fma_f32 v65, v64, s61, -v65
	v_fmac_f32_e32 v65, 0x3377d1cf, v64
	v_fmac_f32_e32 v65, 0x3f317217, v64
	v_cmp_lt_f32_e64 s[10:11], |v64|, s55
	s_nop 1
	v_cndmask_b32_e64 v64, v64, v65, s[10:11]
	v_cndmask_b32_e64 v65, 0, v216, s[8:9]
	v_sub_f32_e32 v64, v64, v65
	v_and_b32_e32 v65, 0xffff0000, v37
	v_mul_f32_e32 v65, 0xbfb8aa3b, v65
	v_exp_f32_e32 v65, v65
	s_nop 0
	v_add_f32_e32 v65, 1.0, v65
	v_rcp_f32_e32 v65, v65
	s_nop 0
	v_fma_f32 v129, v65, v131, v57
	v_cmp_gt_f32_e64 s[8:9], s63, v129
	s_nop 1
	v_cndmask_b32_e64 v65, 0, 32, s[8:9]
	v_ldexp_f32 v65, v129, v65
	v_log_f32_e32 v65, v65
	s_nop 0
	v_mul_f32_e32 v132, 0x3f317217, v65
	v_fma_f32 v132, v65, s61, -v132
	v_fmac_f32_e32 v132, 0x3377d1cf, v65
	v_fmac_f32_e32 v132, 0x3f317217, v65
	v_cmp_lt_f32_e64 s[10:11], |v65|, s55
	s_nop 1
	v_cndmask_b32_e64 v65, v65, v132, s[10:11]
	v_cndmask_b32_e64 v132, 0, v216, s[8:9]
	v_sub_f32_e32 v65, v65, v132
	ds_write_b128 v80, v[58:61]
	ds_write_b128 v80, v[62:65] offset:16
	v_lshlrev_b32_e32 v58, 16, v42
	v_mul_f32_e32 v58, 0xbfb8aa3b, v58
	v_exp_f32_e32 v58, v58
	s_nop 0
	v_add_f32_e32 v58, 1.0, v58
	v_rcp_f32_e32 v58, v58
	s_nop 0
	v_fma_f32 v50, v58, v124, v50
	v_cmp_gt_f32_e64 s[8:9], s63, v50
	s_nop 1
	v_cndmask_b32_e64 v58, 0, 32, s[8:9]
	v_ldexp_f32 v58, v50, v58
	v_log_f32_e32 v58, v58
	s_nop 0
	v_mul_f32_e32 v59, 0x3f317217, v58
	v_fma_f32 v59, v58, s61, -v59
	v_fmac_f32_e32 v59, 0x3377d1cf, v58
	v_fmac_f32_e32 v59, 0x3f317217, v58
	v_cmp_lt_f32_e64 s[10:11], |v58|, s55
	s_nop 1
	v_cndmask_b32_e64 v58, v58, v59, s[10:11]
	v_cndmask_b32_e64 v59, 0, v216, s[8:9]
	v_sub_f32_e32 v58, v58, v59
	v_and_b32_e32 v59, 0xffff0000, v42
	v_mul_f32_e32 v59, 0xbfb8aa3b, v59
	v_exp_f32_e32 v59, v59
	s_nop 0
	v_add_f32_e32 v59, 1.0, v59
	v_rcp_f32_e32 v59, v59
	s_nop 0
	v_fma_f32 v51, v59, v123, v51
	v_cmp_gt_f32_e64 s[8:9], s63, v51
	s_nop 1
	v_cndmask_b32_e64 v59, 0, 32, s[8:9]
	v_ldexp_f32 v59, v51, v59
	v_log_f32_e32 v59, v59
	s_nop 0
	v_mul_f32_e32 v60, 0x3f317217, v59
	v_fma_f32 v60, v59, s61, -v60
	v_fmac_f32_e32 v60, 0x3377d1cf, v59
	v_fmac_f32_e32 v60, 0x3f317217, v59
	v_cmp_lt_f32_e64 s[10:11], |v59|, s55
	s_nop 1
	v_cndmask_b32_e64 v59, v59, v60, s[10:11]
	v_cndmask_b32_e64 v60, 0, v216, s[8:9]
	v_sub_f32_e32 v59, v59, v60
	v_lshlrev_b32_e32 v60, 16, v43
	v_mul_f32_e32 v60, 0xbfb8aa3b, v60
	v_exp_f32_e32 v60, v60
	s_nop 0
	v_add_f32_e32 v60, 1.0, v60
	v_rcp_f32_e32 v60, v60
	s_nop 0
	v_fma_f32 v52, v60, v122, v52
	v_cmp_gt_f32_e64 s[8:9], s63, v52
	s_nop 1
	v_cndmask_b32_e64 v60, 0, 32, s[8:9]
	v_ldexp_f32 v60, v52, v60
	v_log_f32_e32 v60, v60
	s_nop 0
	v_mul_f32_e32 v61, 0x3f317217, v60
	v_fma_f32 v61, v60, s61, -v61
	v_fmac_f32_e32 v61, 0x3377d1cf, v60
	v_fmac_f32_e32 v61, 0x3f317217, v60
	v_cmp_lt_f32_e64 s[10:11], |v60|, s55
	s_nop 1
	v_cndmask_b32_e64 v60, v60, v61, s[10:11]
	v_cndmask_b32_e64 v61, 0, v216, s[8:9]
	v_sub_f32_e32 v60, v60, v61
	v_and_b32_e32 v61, 0xffff0000, v43
	v_mul_f32_e32 v61, 0xbfb8aa3b, v61
	v_exp_f32_e32 v61, v61
	s_nop 0
	v_add_f32_e32 v61, 1.0, v61
	v_rcp_f32_e32 v61, v61
	s_nop 0
	v_fmac_f32_e32 v53, v61, v121
	v_cmp_gt_f32_e64 s[8:9], s63, v53
	s_nop 1
	v_cndmask_b32_e64 v61, 0, 32, s[8:9]
	v_ldexp_f32 v61, v53, v61
	v_log_f32_e32 v61, v61
	s_nop 0
	v_mul_f32_e32 v62, 0x3f317217, v61
	v_fma_f32 v62, v61, s61, -v62
	v_fmac_f32_e32 v62, 0x3377d1cf, v61
	v_fmac_f32_e32 v62, 0x3f317217, v61
	v_cmp_lt_f32_e64 s[10:11], |v61|, s55
	s_nop 1
	v_cndmask_b32_e64 v61, v61, v62, s[10:11]
	v_cndmask_b32_e64 v62, 0, v216, s[8:9]
	v_sub_f32_e32 v61, v61, v62
	v_lshlrev_b32_e32 v62, 16, v44
	v_mul_f32_e32 v62, 0xbfb8aa3b, v62
	v_exp_f32_e32 v62, v62
	s_nop 0
	v_add_f32_e32 v62, 1.0, v62
	v_rcp_f32_e32 v62, v62
	s_nop 0
	v_fma_f32 v54, v62, v125, v54
	v_cmp_gt_f32_e64 s[8:9], s63, v54
	s_nop 1
	v_cndmask_b32_e64 v62, 0, 32, s[8:9]
	v_ldexp_f32 v62, v54, v62
	v_log_f32_e32 v62, v62
	s_nop 0
	v_mul_f32_e32 v63, 0x3f317217, v62
	v_fma_f32 v63, v62, s61, -v63
	v_fmac_f32_e32 v63, 0x3377d1cf, v62
	v_fmac_f32_e32 v63, 0x3f317217, v62
	v_cmp_lt_f32_e64 s[10:11], |v62|, s55
	s_nop 1
	v_cndmask_b32_e64 v62, v62, v63, s[10:11]
	v_cndmask_b32_e64 v63, 0, v216, s[8:9]
	v_sub_f32_e32 v62, v62, v63
	v_and_b32_e32 v63, 0xffff0000, v44
	v_mul_f32_e32 v63, 0xbfb8aa3b, v63
	v_exp_f32_e32 v63, v63
	s_nop 0
	v_add_f32_e32 v63, 1.0, v63
	v_rcp_f32_e32 v63, v63
	s_nop 0
	v_fma_f32 v55, v63, v127, v55
	v_cmp_gt_f32_e64 s[8:9], s63, v55
	s_nop 1
	v_cndmask_b32_e64 v63, 0, 32, s[8:9]
	v_ldexp_f32 v63, v55, v63
	v_log_f32_e32 v63, v63
	s_nop 0
	v_mul_f32_e32 v64, 0x3f317217, v63
	v_fma_f32 v64, v63, s61, -v64
	v_fmac_f32_e32 v64, 0x3377d1cf, v63
	v_fmac_f32_e32 v64, 0x3f317217, v63
	v_cmp_lt_f32_e64 s[10:11], |v63|, s55
	s_nop 1
	v_cndmask_b32_e64 v63, v63, v64, s[10:11]
	v_cndmask_b32_e64 v64, 0, v216, s[8:9]
	v_sub_f32_e32 v63, v63, v64
	v_lshlrev_b32_e32 v64, 16, v45
	v_mul_f32_e32 v64, 0xbfb8aa3b, v64
	v_exp_f32_e32 v64, v64
	s_nop 0
	v_add_f32_e32 v64, 1.0, v64
	v_rcp_f32_e32 v64, v64
	s_nop 0
	v_fma_f32 v56, v64, v130, v56
	v_cmp_gt_f32_e64 s[8:9], s63, v56
	s_nop 1
	v_cndmask_b32_e64 v64, 0, 32, s[8:9]
	v_ldexp_f32 v64, v56, v64
	v_log_f32_e32 v64, v64
	s_nop 0
	v_mul_f32_e32 v65, 0x3f317217, v64
	v_fma_f32 v65, v64, s61, -v65
	v_fmac_f32_e32 v65, 0x3377d1cf, v64
	v_fmac_f32_e32 v65, 0x3f317217, v64
	v_cmp_lt_f32_e64 s[10:11], |v64|, s55
	s_nop 1
	v_cndmask_b32_e64 v64, v64, v65, s[10:11]
	v_cndmask_b32_e64 v65, 0, v216, s[8:9]
	v_sub_f32_e32 v64, v64, v65
	v_and_b32_e32 v65, 0xffff0000, v45
	v_mul_f32_e32 v65, 0xbfb8aa3b, v65
	v_exp_f32_e32 v65, v65
	s_nop 0
	v_add_f32_e32 v65, 1.0, v65
	v_rcp_f32_e32 v65, v65
	s_nop 0
	v_fmac_f32_e32 v57, v65, v131
	v_cmp_gt_f32_e64 s[8:9], s63, v57
	s_nop 1
	v_cndmask_b32_e64 v65, 0, 32, s[8:9]
	v_ldexp_f32 v65, v57, v65
	v_log_f32_e32 v65, v65
	s_nop 0
	v_mul_f32_e32 v121, 0x3f317217, v65
	v_fma_f32 v121, v65, s61, -v121
	v_fmac_f32_e32 v121, 0x3377d1cf, v65
	v_fmac_f32_e32 v121, 0x3f317217, v65
	v_cmp_lt_f32_e64 s[10:11], |v65|, s55
	s_nop 1
	v_cndmask_b32_e64 v65, v65, v121, s[10:11]
	v_cndmask_b32_e64 v121, 0, v216, s[8:9]
	v_sub_f32_e32 v65, v65, v121
	ds_write_b128 v80, v[58:61] offset:16384
	ds_write_b128 v80, v[62:65] offset:16400
	s_waitcnt lgkmcnt(0)
	s_barrier
	ds_read_b32 v58, v100
	s_waitcnt lgkmcnt(0)
	v_add_f32_e32 v58, 0, v58
	ds_write_b32 v100, v58
	ds_read_b32 v59, v101
	s_waitcnt lgkmcnt(0)
	v_add_f32_e32 v58, v58, v59
	ds_write_b32 v101, v58
	ds_read_b32 v59, v102
	s_waitcnt lgkmcnt(0)
	v_add_f32_e32 v58, v58, v59
	ds_write_b32 v102, v58
	ds_read_b32 v59, v103
	s_waitcnt lgkmcnt(0)
	v_add_f32_e32 v58, v58, v59
	ds_write_b32 v103, v58
	ds_read_b32 v59, v104
	s_waitcnt lgkmcnt(0)
	v_add_f32_e32 v58, v58, v59
	ds_write_b32 v104, v58
	ds_read_b32 v59, v105
	s_waitcnt lgkmcnt(0)
	v_add_f32_e32 v58, v58, v59
	ds_write_b32 v105, v58
	ds_read_b32 v59, v106
	s_waitcnt lgkmcnt(0)
	v_add_f32_e32 v58, v58, v59
	ds_write_b32 v106, v58
	ds_read_b32 v59, v107
	s_waitcnt lgkmcnt(0)
	v_add_f32_e32 v58, v58, v59
	ds_write_b32 v107, v58
	ds_read_b32 v59, v108
	s_waitcnt lgkmcnt(0)
	v_add_f32_e32 v58, v58, v59
	ds_write_b32 v108, v58
	ds_read_b32 v59, v109
	s_waitcnt lgkmcnt(0)
	v_add_f32_e32 v58, v58, v59
	ds_write_b32 v109, v58
	ds_read_b32 v59, v110
	s_waitcnt lgkmcnt(0)
	v_add_f32_e32 v58, v58, v59
	ds_write_b32 v110, v58
	ds_read_b32 v59, v111
	s_waitcnt lgkmcnt(0)
	v_add_f32_e32 v58, v58, v59
	ds_write_b32 v111, v58
	ds_read_b32 v59, v112
	s_waitcnt lgkmcnt(0)
	v_add_f32_e32 v58, v58, v59
	ds_write_b32 v112, v58
	ds_read_b32 v59, v113
	s_waitcnt lgkmcnt(0)
	v_add_f32_e32 v58, v58, v59
	ds_write_b32 v113, v58
	ds_read_b32 v59, v114
	s_waitcnt lgkmcnt(0)
	v_add_f32_e32 v58, v58, v59
	ds_write_b32 v114, v58
	ds_read_b32 v59, v115
	s_waitcnt lgkmcnt(0)
	v_add_f32_e32 v58, v58, v59
	v_mov_b32_e32 v59, 0
	ds_write_b32 v115, v58
	ds_write_b32 v77, v58
	s_waitcnt lgkmcnt(0)
	s_barrier
	s_and_saveexec_b64 s[0:1], s[6:7]
	s_cbranch_execz .LBB0_640
	v_mov_b32_e32 v59, 0
	s_mov_b64 s[10:11], 0
	v_mov_b32_e32 v60, v82
	v_mov_b32_e32 v61, v74

.LBB0_746:
	s_cbranch_scc1 .LBB0_752

.LBB0_749:
.LBB0_750:
	ds_read_b128 v[124:127], v227 offset:36864
	ds_read_b128 v[202:205], v227 offset:41472
	ds_read_b128 v[230:233], v227 offset:46080
	ds_read_b128 v[234:237], v227 offset:50688
	s_min_u32 s2, s1, 0xfb
	s_min_u32 s3, s1, 0xfd
	s_nop 1
	v_exp_f32_e32 v229, v128
	v_exp_f32_e32 v252, v144
	v_exp_f32_e32 v14, v129
	v_exp_f32_e32 v0, v145
	s_waitcnt lgkmcnt(3)
	v_mfma_f32_32x32x16_bf16 v[64:79], v[124:127], v[120:123], v[64:79]
	v_add_f32_e32 v15, v229, v252
	v_exp_f32_e32 v213, v130
	v_pk_add_f32 v[128:129], v[14:15], v[0:1]
	v_exp_f32_e32 v214, v146
	v_exp_f32_e32 v206, v131
	ds_read_b128 v[124:127], v227 offset:36896
	ds_read_b128 v[238:241], v227 offset:41504
	ds_read_b128 v[242:245], v227 offset:46112
	ds_read_b128 v[246:249], v227 offset:50720
	s_waitcnt lgkmcnt(6)
	v_mfma_f32_32x32x16_bf16 v[48:63], v[202:205], v[120:123], v[48:63]
	v_add_f32_e64 v202, v128, v128
	v_add_f32_e64 v203, v128, v129
	v_exp_f32_e32 v202, v147
	v_add_f32_e32 v207, v213, v214
	s_lshl_b32 s2, s2, 17
	v_max_i32_e32 v15, v14, v0
	s_add_i32 s42, s2, 0x80000
	s_lshl_b32 s2, s3, 14
	s_waitcnt lgkmcnt(5)
	v_mfma_f32_32x32x16_bf16 v[32:47], v[230:233], v[120:123], v[32:47]
	v_max3_i32 v15, v229, v252, v15
	v_max_i32_e32 v128, v213, v214
	v_lshl_add_u64 v[250:251], v[192:193], 0, s[42:43]
	v_lshl_add_u64 v[180:181], v[196:197], 0, s[42:43]
	s_add_i32 s42, s2, 0x8000
	v_lshl_add_u64 v[182:183], v[194:195], 0, s[42:43]
	v_lshl_add_u64 v[184:185], v[198:199], 0, s[42:43]
	s_waitcnt lgkmcnt(4)
	v_mfma_f32_32x32x16_bf16 v[16:31], v[234:237], v[120:123], v[16:31]
	v_add_f32_e64 v120, v206, v202
	v_add_f32_e64 v121, v207, v203
	v_add_f32_e64 v204, v120, v120
	v_add_f32_e64 v205, v120, v121
	v_max_i32_e32 v120, v206, v202
	v_max3_i32 v15, v15, v128, v120
	ds_read_b128 v[120:123], v227 offset:36928
	ds_read_b128 v[230:233], v227 offset:41536
	ds_read_b128 v[234:237], v227 offset:46144
	ds_read_b128 v[176:179], v227 offset:50752
	s_waitcnt vmcnt(3)
	ds_write_b128 v221, v[10:13] offset:18432
	s_waitcnt vmcnt(2)
	ds_write_b128 v221, v[112:115] offset:23040
	s_waitcnt vmcnt(1)
	ds_write_b128 v222, v[168:171] offset:55296
	s_waitcnt vmcnt(0)
	ds_write_b128 v222, v[172:175] offset:64512
	global_load_dwordx4 v[128:131], v[250:251], off
	global_load_dwordx4 v[144:147], v[180:181], off
	global_load_dwordx4 v[168:171], v[182:183], off
	global_load_dwordx4 v[172:175], v[184:185], off
	v_exp_f32_e32 v203, v132
	v_exp_f32_e32 v207, v148
	v_exp_f32_e32 v180, v133
	v_exp_f32_e32 v204, v149
	s_waitcnt lgkmcnt(11)
	v_mfma_f32_32x32x16_bf16 v[64:79], v[124:127], v[116:119], v[64:79]
	v_add_f32_e32 v181, v203, v207
	v_max_i32_e32 v12, v203, v207
	v_add_f32_e64 v10, v180, v204
	v_add_f32_e64 v11, v181, v205
	v_exp_f32_e32 v181, v134
	v_exp_f32_e32 v205, v150
	v_pk_add_f32 v[182:183], v[10:11], v[10:11] op_sel_hi:[0,1]
	v_max_i32_e32 v10, v180, v204
	s_waitcnt lgkmcnt(10)
	v_mfma_f32_32x32x16_bf16 v[48:63], v[238:241], v[116:119], v[48:63]
	v_max3_i32 v15, v15, v12, v10
	v_max_i32_e32 v126, v181, v205
	v_add_f32_e32 v185, v181, v205
	s_waitcnt lgkmcnt(9)
	v_mfma_f32_32x32x16_bf16 v[32:47], v[242:245], v[116:119], v[32:47]
	s_waitcnt lgkmcnt(8)
	v_mfma_f32_32x32x16_bf16 v[16:31], v[246:249], v[116:119], v[16:31]
	v_exp_f32_e32 v184, v135
	v_exp_f32_e32 v182, v151
	s_waitcnt lgkmcnt(7)
	v_mfma_f32_32x32x16_bf16 v[64:79], v[120:123], v[6:9], v[64:79]
	ds_read_b128 v[10:13], v227 offset:36960
	ds_read_b128 v[112:115], v227 offset:41568
	ds_read_b128 v[116:119], v227 offset:46176
	ds_read_b128 v[120:123], v227 offset:50784
	v_add_f32_e64 v124, v184, v182
	v_add_f32_e64 v125, v185, v183
	v_exp_f32_e32 v183, v136
	v_exp_f32_e32 v185, v152
	s_waitcnt lgkmcnt(10)
	v_mfma_f32_32x32x16_bf16 v[48:63], v[230:233], v[6:9], v[48:63]
	v_add_f32_e64 v230, v124, v124
	v_add_f32_e64 v231, v124, v125
	v_exp_f32_e32 v232, v137
	v_exp_f32_e32 v230, v153
	v_max_i32_e32 v124, v184, v182
	v_add_f32_e32 v233, v183, v185
	v_max3_i32 v15, v15, v126, v124
	v_pk_add_f32 v[124:125], v[232:233], v[230:231]
	s_waitcnt lgkmcnt(9)
	v_mfma_f32_32x32x16_bf16 v[32:47], v[234:237], v[6:9], v[32:47]
	v_max_i32_e32 v126, v183, v185
	v_add_f32_e64 v234, v124, v124
	v_add_f32_e64 v235, v124, v125
	v_max_i32_e32 v124, v232, v230
	v_max3_i32 v15, v15, v126, v124
	s_waitcnt lgkmcnt(8)
	v_mfma_f32_32x32x16_bf16 v[16:31], v[176:179], v[6:9], v[16:31]
	v_exp_f32_e32 v231, v138
	v_exp_f32_e32 v233, v154
	s_waitcnt lgkmcnt(3)
	v_mfma_f32_32x32x16_bf16 v[64:79], v[10:13], v[2:5], v[64:79]
	v_exp_f32_e32 v236, v139
	v_exp_f32_e32 v234, v155
	ds_read_b128 v[6:9], v223
	ds_read_b128 v[10:13], v223 offset:32
	ds_read_b128 v[132:135], v223 offset:4608
	ds_read_b128 v[148:151], v223 offset:4640
	v_add_f32_e32 v237, v231, v233
	v_exp_f32_e32 v156, v156
	s_waitcnt lgkmcnt(6)
	v_mfma_f32_32x32x16_bf16 v[48:63], v[112:115], v[2:5], v[48:63]
	v_add_f32_e64 v112, v236, v234
	v_add_f32_e64 v113, v237, v235
	v_exp_f32_e32 v235, v140
	v_max_i32_e32 v114, v231, v233
	v_pk_add_f32 v[238:239], v[112:113], v[112:113] op_sel_hi:[0,1]
	v_max_i32_e32 v112, v236, v234
	v_max3_i32 v15, v15, v114, v112
	v_add_f32_e32 v241, v235, v156
	s_waitcnt lgkmcnt(5)
	v_mfma_f32_32x32x16_bf16 v[32:47], v[116:119], v[2:5], v[32:47]
	v_max_i32_e32 v237, v235, v156
	s_waitcnt lgkmcnt(4)
	v_mfma_f32_32x32x16_bf16 v[16:31], v[120:123], v[2:5], v[16:31]
	s_waitcnt lgkmcnt(3)
	v_mfma_f32_32x32x16_bf16 v[112:127], v[6:9], v[160:163], v[96:111]
	v_exp_f32_e32 v240, v141
	v_exp_f32_e32 v238, v157
	v_exp_f32_e32 v158, v158
	ds_read_b128 v[2:5], v223 offset:64
	ds_read_b128 v[136:139], v223 offset:96
	ds_read_b128 v[6:9], v223 offset:4672
	ds_read_b128 v[152:155], v223 offset:4704
	v_pk_add_f32 v[140:141], v[240:241], v[238:239]
	s_nop 0
	v_pk_add_f32 v[140:141], v[140:141], v[140:141] op_sel_hi:[0,1]
	s_waitcnt lgkmcnt(5)
	v_mfma_f32_32x32x16_bf16 v[80:95], v[132:135], v[160:163], v[96:111]
	v_exp_f32_e32 v239, v142
	v_exp_f32_e32 v142, v143
	v_exp_f32_e32 v140, v159
	ds_read_b128 v[132:135], v224
	ds_read_b128 v[176:179], v224 offset:1024
	v_add_f32_e32 v143, v239, v158
	v_max_i32_e32 v157, v240, v238
	v_mfma_f32_32x32x16_bf16 v[112:127], v[10:13], v[164:167], v[112:127]
	v_add_f32_e64 v10, v142, v140
	v_add_f32_e64 v11, v143, v141
	v_max3_i32 v12, v15, v237, v157
	v_max_i32_e32 v13, v239, v158
	v_add_f32_e32 v141, v10, v11
	v_max_i32_e32 v10, v142, v140
	v_max3_i32 v15, v12, v13, v10
	s_waitcnt lgkmcnt(6)
	v_mfma_f32_32x32x16_bf16 v[80:95], v[148:151], v[164:167], v[80:95]
	s_waitcnt lgkmcnt(1)
	v_mfma_f32_32x32x16_bf16 v[112:127], v[2:5], v[132:135], v[112:127]
	v_cvt_pk_bf16_f32 v10, v229, v14
	v_cvt_pk_bf16_f32 v11, v213, v206
	v_cvt_pk_bf16_f32 v12, v203, v180
	v_cvt_pk_bf16_f32 v13, v181, v184
	v_cvt_pk_bf16_f32 v2, v252, v0
	v_cvt_pk_bf16_f32 v3, v214, v202
	v_cvt_pk_bf16_f32 v4, v207, v204
	v_mfma_f32_32x32x16_bf16 v[80:95], v[6:9], v[132:135], v[80:95]
	v_cvt_pk_bf16_f32 v6, v183, v232
	v_cvt_pk_bf16_f32 v7, v231, v236
	v_cvt_pk_bf16_f32 v8, v235, v240
	v_cvt_pk_bf16_f32 v9, v239, v142
	v_cvt_pk_bf16_f32 v5, v205, v182
	v_cvt_pk_bf16_f32 v132, v185, v230
	v_cvt_pk_bf16_f32 v133, v233, v234
	s_waitcnt lgkmcnt(0)
	v_mfma_f32_32x32x16_bf16 v[112:127], v[136:139], v[176:179], v[112:127]
	v_cvt_pk_bf16_f32 v134, v156, v238
	v_cvt_pk_bf16_f32 v135, v158, v140
	v_mfma_f32_32x32x16_bf16 v[80:95], v[152:155], v[176:179], v[80:95]
	v_add_f32_e32 v204, v228, v141
	v_cmp_lt_i32_e32 vcc, s64, v15
	s_mov_b64 s[2:3], 0x8000
	v_lshl_add_u64 v[200:201], v[200:201], 0, s[2:3]
	s_cmpk_gt_u32 s1, 0xfd
	s_barrier
	s_cbranch_vccz .LBB0_746
	v_max_i32_e32 v0, 0, v15
	ds_bpermute_b32 v14, v189, v0
	v_and_b32_e32 v15, 0xffff0000, v10
	s_waitcnt lgkmcnt(0)
	v_max_i32_e32 v0, v0, v14
	v_log_f32_e32 v0, v0
	v_lshlrev_b32_e32 v14, 16, v10
	v_max_f32_e32 v97, 0, v0
	v_exp_f32_e64 v0, -v97
	v_add_f32_e32 v226, v226, v97
	v_xor_b32_e32 v96, 0x80000000, v226
	v_sub_f32_e32 v95, v95, v97
	v_pk_mul_f32 v[14:15], v[0:1], v[14:15] op_sel_hi:[0,1]
	v_cvt_pk_bf16_f32 v10, v14, v15
	v_lshlrev_b32_e32 v14, 16, v11
	v_and_b32_e32 v15, 0xffff0000, v11
	v_pk_mul_f32 v[14:15], v[0:1], v[14:15] op_sel_hi:[0,1]
	v_cvt_pk_bf16_f32 v11, v14, v15
	v_lshlrev_b32_e32 v14, 16, v12
	v_and_b32_e32 v15, 0xffff0000, v12
	v_pk_mul_f32 v[14:15], v[0:1], v[14:15] op_sel_hi:[0,1]
	v_cvt_pk_bf16_f32 v12, v14, v15
	v_lshlrev_b32_e32 v14, 16, v13
	v_and_b32_e32 v15, 0xffff0000, v13
	v_pk_mul_f32 v[14:15], v[0:1], v[14:15] op_sel_hi:[0,1]
	v_cvt_pk_bf16_f32 v13, v14, v15
	v_lshlrev_b32_e32 v14, 16, v6
	v_and_b32_e32 v15, 0xffff0000, v6
	v_pk_mul_f32 v[14:15], v[0:1], v[14:15] op_sel_hi:[0,1]
	v_cvt_pk_bf16_f32 v6, v14, v15
	v_lshlrev_b32_e32 v14, 16, v7
	v_and_b32_e32 v15, 0xffff0000, v7
	v_pk_mul_f32 v[14:15], v[0:1], v[14:15] op_sel_hi:[0,1]
	v_cvt_pk_bf16_f32 v7, v14, v15
	v_lshlrev_b32_e32 v14, 16, v8
	v_and_b32_e32 v15, 0xffff0000, v8
	v_pk_mul_f32 v[14:15], v[0:1], v[14:15] op_sel_hi:[0,1]
	v_cvt_pk_bf16_f32 v8, v14, v15
	v_lshlrev_b32_e32 v14, 16, v9
	v_and_b32_e32 v15, 0xffff0000, v9
	v_pk_mul_f32 v[14:15], v[0:1], v[14:15] op_sel_hi:[0,1]
	v_cvt_pk_bf16_f32 v9, v14, v15
	v_lshlrev_b32_e32 v14, 16, v2
	v_and_b32_e32 v15, 0xffff0000, v2
	v_pk_mul_f32 v[14:15], v[0:1], v[14:15] op_sel_hi:[0,1]
	v_cvt_pk_bf16_f32 v2, v14, v15
	v_lshlrev_b32_e32 v14, 16, v3
	v_and_b32_e32 v15, 0xffff0000, v3
	v_pk_mul_f32 v[14:15], v[0:1], v[14:15] op_sel_hi:[0,1]
	v_cvt_pk_bf16_f32 v3, v14, v15
	v_lshlrev_b32_e32 v14, 16, v4
	v_and_b32_e32 v15, 0xffff0000, v4
	v_pk_mul_f32 v[14:15], v[0:1], v[14:15] op_sel_hi:[0,1]
	v_cvt_pk_bf16_f32 v4, v14, v15
	v_lshlrev_b32_e32 v14, 16, v5
	v_and_b32_e32 v15, 0xffff0000, v5
	v_pk_mul_f32 v[14:15], v[0:1], v[14:15] op_sel_hi:[0,1]
	v_cvt_pk_bf16_f32 v5, v14, v15
	v_lshlrev_b32_e32 v14, 16, v132
	v_and_b32_e32 v15, 0xffff0000, v132
	v_pk_mul_f32 v[14:15], v[0:1], v[14:15] op_sel_hi:[0,1]
	v_cvt_pk_bf16_f32 v132, v14, v15
	v_lshlrev_b32_e32 v14, 16, v133
	v_and_b32_e32 v15, 0xffff0000, v133
	v_pk_mul_f32 v[14:15], v[0:1], v[14:15] op_sel_hi:[0,1]
	v_cvt_pk_bf16_f32 v133, v14, v15
	v_lshlrev_b32_e32 v14, 16, v134
	v_and_b32_e32 v15, 0xffff0000, v134
	v_pk_mul_f32 v[14:15], v[0:1], v[14:15] op_sel_hi:[0,1]
	v_cvt_pk_bf16_f32 v134, v14, v15
	v_lshlrev_b32_e32 v14, 16, v135
	v_and_b32_e32 v15, 0xffff0000, v135
	v_pk_mul_f32 v[14:15], v[0:1], v[14:15] op_sel_hi:[0,1]
	v_pk_mul_f32 v[78:79], v[78:79], v[0:1] op_sel_hi:[1,0]
	v_pk_mul_f32 v[76:77], v[76:77], v[0:1] op_sel_hi:[1,0]
	v_pk_mul_f32 v[74:75], v[74:75], v[0:1] op_sel_hi:[1,0]
	v_pk_mul_f32 v[72:73], v[72:73], v[0:1] op_sel_hi:[1,0]
	v_pk_mul_f32 v[70:71], v[70:71], v[0:1] op_sel_hi:[1,0]
	v_pk_mul_f32 v[68:69], v[68:69], v[0:1] op_sel_hi:[1,0]
	v_pk_mul_f32 v[66:67], v[66:67], v[0:1] op_sel_hi:[1,0]
	v_pk_mul_f32 v[64:65], v[64:65], v[0:1] op_sel_hi:[1,0]
	v_pk_mul_f32 v[62:63], v[62:63], v[0:1] op_sel_hi:[1,0]
	v_pk_mul_f32 v[60:61], v[60:61], v[0:1] op_sel_hi:[1,0]
	v_pk_mul_f32 v[58:59], v[58:59], v[0:1] op_sel_hi:[1,0]
	v_pk_mul_f32 v[56:57], v[56:57], v[0:1] op_sel_hi:[1,0]
	v_pk_mul_f32 v[54:55], v[54:55], v[0:1] op_sel_hi:[1,0]
	v_pk_mul_f32 v[52:53], v[52:53], v[0:1] op_sel_hi:[1,0]
	v_pk_mul_f32 v[50:51], v[50:51], v[0:1] op_sel_hi:[1,0]
	v_pk_mul_f32 v[48:49], v[48:49], v[0:1] op_sel_hi:[1,0]
	v_pk_mul_f32 v[46:47], v[46:47], v[0:1] op_sel_hi:[1,0]
	v_pk_mul_f32 v[44:45], v[44:45], v[0:1] op_sel_hi:[1,0]
	v_pk_mul_f32 v[42:43], v[42:43], v[0:1] op_sel_hi:[1,0]
	v_pk_mul_f32 v[40:41], v[40:41], v[0:1] op_sel_hi:[1,0]
	v_pk_mul_f32 v[38:39], v[38:39], v[0:1] op_sel_hi:[1,0]
	v_pk_mul_f32 v[36:37], v[36:37], v[0:1] op_sel_hi:[1,0]
	v_pk_mul_f32 v[34:35], v[34:35], v[0:1] op_sel_hi:[1,0]
	v_pk_mul_f32 v[32:33], v[32:33], v[0:1] op_sel_hi:[1,0]
	v_pk_mul_f32 v[30:31], v[30:31], v[0:1] op_sel_hi:[1,0]
	v_pk_mul_f32 v[28:29], v[28:29], v[0:1] op_sel_hi:[1,0]
	v_pk_mul_f32 v[26:27], v[26:27], v[0:1] op_sel_hi:[1,0]
	v_pk_mul_f32 v[24:25], v[24:25], v[0:1] op_sel_hi:[1,0]
	v_pk_mul_f32 v[22:23], v[22:23], v[0:1] op_sel_hi:[1,0]
	v_pk_mul_f32 v[20:21], v[20:21], v[0:1] op_sel_hi:[1,0]
	v_pk_mul_f32 v[18:19], v[18:19], v[0:1] op_sel_hi:[1,0]
	v_pk_mul_f32 v[16:17], v[16:17], v[0:1] op_sel_hi:[1,0]
	v_sub_f32_e32 v94, v94, v97
	v_sub_f32_e32 v93, v93, v97
	v_sub_f32_e32 v92, v92, v97
	v_sub_f32_e32 v91, v91, v97
	v_sub_f32_e32 v90, v90, v97
	v_sub_f32_e32 v89, v89, v97
	v_sub_f32_e32 v88, v88, v97
	v_sub_f32_e32 v87, v87, v97
	v_sub_f32_e32 v86, v86, v97
	v_sub_f32_e32 v85, v85, v97
	v_sub_f32_e32 v84, v84, v97
	v_sub_f32_e32 v83, v83, v97
	v_sub_f32_e32 v82, v82, v97
	v_sub_f32_e32 v81, v81, v97
	v_sub_f32_e32 v80, v80, v97
	v_cvt_pk_bf16_f32 v135, v14, v15
	v_sub_f32_e32 v127, v127, v97
	v_sub_f32_e32 v126, v126, v97
	v_sub_f32_e32 v125, v125, v97
	v_sub_f32_e32 v124, v124, v97
	v_sub_f32_e32 v123, v123, v97
	v_sub_f32_e32 v122, v122, v97
	v_sub_f32_e32 v121, v121, v97
	v_sub_f32_e32 v120, v120, v97
	v_sub_f32_e32 v119, v119, v97
	v_sub_f32_e32 v118, v118, v97
	v_sub_f32_e32 v117, v117, v97
	v_sub_f32_e32 v116, v116, v97
	v_sub_f32_e32 v115, v115, v97
	v_sub_f32_e32 v114, v114, v97
	v_sub_f32_e32 v113, v113, v97
	v_sub_f32_e32 v112, v112, v97
	v_mul_f32_e32 v204, v204, v0
	v_mov_b32_e32 v97, v96
	v_mov_b32_e32 v98, v96
	v_mov_b32_e32 v99, v96
	v_mov_b32_e32 v100, v96
	v_mov_b32_e32 v101, v96
	v_mov_b32_e32 v102, v96
	v_mov_b32_e32 v103, v96
	v_mov_b32_e32 v104, v96
	v_mov_b32_e32 v105, v96
	v_mov_b32_e32 v106, v96
	v_mov_b32_e32 v107, v96
	v_mov_b32_e32 v108, v96
	v_mov_b32_e32 v109, v96
	v_mov_b32_e32 v110, v96
	v_mov_b32_e32 v111, v96
	s_branch .LBB0_746

.LBB0_761:
	s_ashr_i32 s2, s12, 6
	s_waitcnt vmcnt(0)
	v_mov_b32_e32 v42, v212
	s_lshl_b32 s10, s2, 7
	s_ashr_i32 s11, s10, 31
	v_readfirstlane_b32 s1, v42
	s_and_b32 s18, s12, 63
	s_ashr_i32 s0, s1, 6
	s_lshl_b64 s[14:15], s[10:11], 2
	v_readlane_b32 s3, v253, 32
	s_add_u32 s4, s3, s14
	v_readlane_b32 s3, v253, 33
	s_addc_u32 s5, s3, s15
	s_lshl_b32 s19, s2, 1
	s_lshl_b32 s3, s18, 4
	s_ashr_i32 s20, s19, 31
	s_add_u32 s2, s3, s19
	s_addc_u32 s3, 0, s20
	s_lshl_b64 s[2:3], s[2:3], 16
	s_add_u32 s6, s74, s2
	v_bfe_u32 v44, v42, 5, 1
	s_addc_u32 s7, s75, s3
	s_ashr_i32 s2, s1, 7
	v_and_b32_e32 v43, 31, v42
	s_lshl_b32 s8, s2, 12
	v_lshlrev_b32_e32 v0, 9, v44
	s_and_b32 s3, s1, 64
	v_or3_b32 v0, v0, s8, v43
	v_or_b32_e32 v16, s3, v0
	v_ashrrev_i32_e32 v17, 31, v16
	v_lshl_add_u64 v[8:9], v[16:17], 2, s[6:7]
	s_movk_i32 s8, 0x1000
	v_add_co_u32_e32 v14, vcc, s8, v8
	s_movk_i32 s9, 0x3000
	s_nop 0
	v_addc_co_u32_e32 v15, vcc, 0, v9, vcc
	v_add_co_u32_e32 v18, vcc, s33, v8
	global_load_dword v2, v[8:9], off
	global_load_dword v3, v[8:9], off offset:512
	global_load_dword v4, v[8:9], off offset:1024
	global_load_dword v5, v[8:9], off offset:1536
	v_addc_co_u32_e32 v19, vcc, 0, v9, vcc
	global_load_dword v6, v[18:19], off offset:-4096
	global_load_dword v10, v[18:19], off
	global_load_dword v11, v[18:19], off offset:512
	global_load_dword v12, v[18:19], off offset:1024
	global_load_dword v13, v[18:19], off offset:1536
	v_add_co_u32_e32 v18, vcc, s9, v8
	v_ashrrev_i32_e32 v17, 31, v0
	s_nop 0
	v_addc_co_u32_e32 v19, vcc, 0, v9, vcc
	v_lshl_add_u64 v[30:31], v[16:17], 2, s[6:7]
	global_load_dword v7, v[14:15], off offset:512
	global_load_dword v8, v[14:15], off offset:1024
	global_load_dword v9, v[14:15], off offset:1536
	s_nop 0
	global_load_dword v14, v[18:19], off
	v_add_co_u32_e32 v26, vcc, s8, v30
	v_add_u32_e32 v51, 0x200, v42
	s_nop 0
	v_addc_co_u32_e32 v27, vcc, 0, v31, vcc
	global_load_dword v15, v[18:19], off offset:512
	global_load_dword v16, v[18:19], off offset:1024
	global_load_dword v17, v[18:19], off offset:1536
	s_nop 0
	global_load_dword v18, v[30:31], off offset:128
	global_load_dword v19, v[30:31], off offset:640
	global_load_dword v20, v[30:31], off offset:1152
	global_load_dword v21, v[30:31], off offset:1664
	global_load_dword v22, v[26:27], off offset:128
	v_add_co_u32_e32 v32, vcc, s33, v30
	s_lshl_b32 s8, s18, 8
	s_nop 0
	v_addc_co_u32_e32 v33, vcc, 0, v31, vcc
	global_load_dword v23, v[26:27], off offset:640
	global_load_dword v24, v[26:27], off offset:1152
	global_load_dword v25, v[26:27], off offset:1664
	s_nop 0
	global_load_dword v26, v[32:33], off offset:128
	global_load_dword v27, v[32:33], off offset:640
	global_load_dword v28, v[32:33], off offset:1152
	global_load_dword v29, v[32:33], off offset:1664
	v_add_co_u32_e32 v34, vcc, s9, v30
	v_lshlrev_b32_e32 v36, 3, v42
	s_nop 0
	v_addc_co_u32_e32 v35, vcc, 0, v31, vcc
	global_load_dword v30, v[34:35], off offset:128
	global_load_dword v31, v[34:35], off offset:640
	global_load_dword v32, v[34:35], off offset:1152
	global_load_dword v33, v[34:35], off offset:1664
	v_ashrrev_i32_e32 v128, 4, v51
	v_and_b32_e32 v50, 0x78, v36
	v_add_u32_e32 v36, s8, v128
	v_ashrrev_i32_e32 v37, 31, v36
	v_or_b32_e32 v122, s10, v50
	v_mov_b32_e32 v123, s11
	v_lshlrev_b64 v[36:37], 10, v[36:37]
	s_lshl_b32 s6, s2, 6
	v_readlane_b32 s16, v255, 5
	v_lshl_add_u64 v[36:37], v[36:37], 0, v[122:123]
	v_lshlrev_b32_e32 v46, 3, v44
	v_or_b32_e32 v47, s3, v43
	s_add_i32 s3, s16, s6
	v_lshlrev_b64 v[36:37], 1, v[36:37]
	v_add_u32_e32 v49, s3, v46
	s_movk_i32 s23, 0x110
	v_lshl_add_u64 v[38:39], s[86:87], 0, v[36:37]
	v_mad_u32_u24 v0, v47, s23, v49
	global_load_dwordx4 v[66:69], v[38:39], off
	v_or_b32_e32 v52, 32, v47
	v_ashrrev_i32_e32 v129, 4, v42
	v_readlane_b32 s9, v255, 3
	s_and_b32 s3, s1, 0xffffff80
	s_ashr_i32 s26, s1, 8
	s_lshl_b32 s1, s0, 5
	v_mov_b32_e32 v54, s16
	v_lshrrev_b32_e32 v51, 7, v51
	s_add_i32 s21, 0, 0x1a000
	v_readlane_b32 s13, v255, 4
	v_xor_b32_e32 v51, v51, v42
	v_readlane_b32 s27, v255, 2
	s_add_i32 s25, s13, s3
	s_movk_i32 s22, 0x90
	v_lshlrev_b32_e32 v56, 1, v129
	v_lshlrev_b32_e32 v51, 4, v51
	v_lshlrev_b32_e32 v58, 1, v128
	v_lshl_or_b32 v136, s26, 5, v43
	v_and_b32_e32 v56, 14, v56
	v_and_b32_e32 v51, 0x70, v51
	v_and_b32_e32 v58, 14, v58
	v_or_b32_e32 v60, 2, v44
	v_or_b32_e32 v63, 4, v44
	v_or_b32_e32 v90, 6, v44
	v_and_b32_e32 v45, 63, v42
	v_mul_u32_u24_e32 v48, 0x110, v47
	v_ashrrev_i32_e32 v130, 7, v42
	v_mul_lo_u32 v55, v136, s23
	v_mad_u32_u24 v47, v47, s22, 0
	v_mad_u32_u24 v92, v52, s22, 0
	s_waitcnt vmcnt(31)
	v_cvt_pk_bf16_f32 v34, v2, v3
	v_mul_u32_u24_e32 v53, 0x110, v52
	s_waitcnt vmcnt(29)
	v_cvt_pk_bf16_f32 v35, v4, v5
	v_lshlrev_b32_e32 v133, 4, v44
	v_add_u32_e32 v55, 0, v55
	v_lshlrev_b32_e32 v57, 9, v128
	s_mov_b32 s24, 0
	v_cmp_lt_i32_e64 s[6:7], 0, v130
	v_add_u32_e32 v149, v55, v133
	s_waitcnt vmcnt(23)
	v_cvt_pk_bf16_f32 v38, v6, v7
	v_add_u32_e32 v158, v49, v48
	s_waitcnt vmcnt(21)
	v_cvt_pk_bf16_f32 v39, v8, v9
	ds_write2_b64 v0, v[34:35], v[38:39] offset1:2
	v_cvt_pk_bf16_f32 v34, v10, v11
	v_cvt_pk_bf16_f32 v35, v12, v13
	s_waitcnt vmcnt(19)
	v_cvt_pk_bf16_f32 v38, v14, v15
	s_waitcnt vmcnt(17)
	v_cvt_pk_bf16_f32 v39, v16, v17
	ds_write2_b64 v0, v[34:35], v[38:39] offset0:4 offset1:6
	v_mad_u32_u24 v0, v52, s23, v49
	s_waitcnt vmcnt(15)
	v_cvt_pk_bf16_f32 v34, v18, v19
	s_waitcnt vmcnt(13)
	v_cvt_pk_bf16_f32 v35, v20, v21
	s_waitcnt vmcnt(11)
	v_cvt_pk_bf16_f32 v38, v22, v23
	s_waitcnt vmcnt(9)
	v_cvt_pk_bf16_f32 v39, v24, v25
	ds_write2_b64 v0, v[34:35], v[38:39] offset1:2
	v_add_u32_e32 v38, s8, v129
	v_ashrrev_i32_e32 v39, 31, v38
	v_lshlrev_b64 v[38:39], 10, v[38:39]
	v_lshl_add_u64 v[38:39], v[38:39], 0, v[122:123]
	v_lshlrev_b64 v[38:39], 1, v[38:39]
	v_lshl_add_u64 v[40:41], s[88:89], 0, v[38:39]
	s_waitcnt vmcnt(7)
	v_cvt_pk_bf16_f32 v34, v26, v27
	s_waitcnt vmcnt(5)
	v_cvt_pk_bf16_f32 v35, v28, v29
	global_load_dwordx4 v[70:73], v[40:41], off
	s_waitcnt vmcnt(4)
	v_cvt_pk_bf16_f32 v40, v30, v31
	s_waitcnt vmcnt(2)
	v_cvt_pk_bf16_f32 v41, v32, v33
	ds_write2_b64 v0, v[34:35], v[40:41] offset0:4 offset1:6
	v_lshl_add_u64 v[34:35], s[76:77], 0, v[38:39]
	v_lshl_add_u64 v[38:39], s[86:87], 0, v[38:39]
	global_load_dwordx4 v[74:77], v[34:35], off
	global_load_dwordx4 v[78:81], v[38:39], off
	v_lshl_add_u64 v[34:35], s[88:89], 0, v[36:37]
	v_lshl_add_u64 v[36:37], s[76:77], 0, v[36:37]
	global_load_dwordx4 v[82:85], v[34:35], off
	global_load_dwordx4 v[86:89], v[36:37], off
	v_lshlrev_b32_e32 v35, 2, v42
	v_lshlrev_b32_e32 v0, 2, v50
	v_and_b32_e32 v36, 0x1fc, v35
	v_add_u32_e32 v132, s9, v0
	v_add_u32_e32 v135, s9, v36
	s_and_b32 s9, s1, 0x60
	v_or_b32_e32 v41, s9, v43
	v_mad_u32_u24 v54, v41, s23, v54
	v_bfe_u32 v137, v41, 3, 3
	v_mul_u32_u24_e32 v41, 0x90, v41
	v_add3_u32 v138, 0, v41, v46
	v_lshrrev_b32_e32 v46, 7, v42
	v_xor_b32_e32 v46, v46, v42
	v_lshl_add_u64 v[124:125], s[4:5], 0, v[0:1]
	global_load_dwordx4 v[236:239], v[124:125], off
	global_load_dwordx4 v[240:243], v[124:125], off offset:16
	v_add_u32_e32 v34, s21, v0
	v_lshl_or_b32 v0, s2, 5, v43
	v_add_u32_e32 v134, s13, v36
	s_ashr_i32 s13, s12, 31
	s_ashr_i32 s1, s0, 31
	v_lshlrev_b32_e32 v46, 4, v46
	v_add_u32_e32 v131, s27, v35
	v_lshl_add_u32 v35, v50, 1, 0
	v_mul_lo_u32 v39, v0, s22
	v_lshrrev_b32_e32 v0, 3, v0
	s_lshl_b64 s[2:3], s[12:13], 16
	s_lshl_b64 s[0:1], s[0:1], 13
	v_and_b32_e32 v46, 0x70, v46
	v_mul_u32_u24_e32 v50, 0x90, v50
	v_bfe_u32 v40, v42, 3, 3
	s_cmp_gt_i32 s26, -1
	v_lshlrev_b32_e32 v41, 5, v42
	v_or3_b32 v46, v46, v56, v50
	v_mul_lo_u32 v56, v129, s23
	v_or3_b32 v50, v51, v58, v50
	v_mul_lo_u32 v51, v128, s23
	v_bfe_u32 v42, v42, 3, 2
	v_bitop3_b32 v58, v0, v44, 7 bitop3:0x6c
	v_bitop3_b32 v61, v0, v60, 7 bitop3:0x6c
	v_bitop3_b32 v64, v0, v63, 7 bitop3:0x6c
	v_bitop3_b32 v0, v0, v90, 7 bitop3:0x6c
	v_readlane_b32 s22, v253, 8
	s_cselect_b64 s[16:17], -1, 0
	v_lshlrev_b32_e32 v91, 4, v0
	v_bitop3_b32 v0, v44, v42, 6 bitop3:0x36
	v_readlane_b32 s23, v253, 9
	s_add_u32 s22, s22, s2
	v_xor_b32_e32 v59, v44, v42
	v_bitop3_b32 v62, v44, v42, 2 bitop3:0x36
	v_bitop3_b32 v65, v44, v42, 4 bitop3:0x36
	v_lshlrev_b32_e32 v42, 4, v0
	v_lshrrev_b32_e32 v0, 3, v52
	s_addc_u32 s23, s23, s3
	v_bitop3_b32 v44, v0, v44, 7 bitop3:0x6c
	v_bitop3_b32 v52, v0, v60, 7 bitop3:0x6c
	v_bitop3_b32 v60, v0, v63, 7 bitop3:0x6c
	v_bitop3_b32 v0, v0, v90, 7 bitop3:0x6c
	s_add_u32 s0, s22, s0
	v_and_b32_e32 v41, 0xfffffe00, v41
	v_lshlrev_b32_e32 v63, 4, v0
	s_addc_u32 s1, s23, s1
	v_lshlrev_b32_e32 v0, 4, v45
	v_add_u32_e32 v37, s21, v36
	v_lshlrev_b32_e32 v38, 13, v130
	v_add_u32_e32 v39, 0, v39
	v_add_u32_e32 v139, v34, v41
	v_lshlrev_b32_e32 v41, 9, v129
	v_lshlrev_b32_e32 v58, 4, v58
	v_lshlrev_b32_e32 v59, 4, v59
	v_lshlrev_b32_e32 v61, 4, v61
	v_lshlrev_b32_e32 v62, 4, v62
	v_lshlrev_b32_e32 v64, 4, v64
	v_lshlrev_b32_e32 v65, 4, v65
	v_lshlrev_b32_e32 v44, 4, v44
	v_lshlrev_b32_e32 v52, 4, v52
	v_lshlrev_b32_e32 v60, 4, v60
	v_lshl_add_u64 v[126:127], s[0:1], 0, v[0:1]
	v_add_u32_e32 v0, s27, v36
	v_mul_u32_u24_e32 v36, 0x110, v43
	v_readlane_b32 s0, v255, 6
	v_cmp_eq_u32_e64 s[4:5], 3, v130
	s_or_b32 s13, s8, 64
	s_add_i32 s26, s26, 1
	v_or_b32_e32 v140, 27, v40
	v_add3_u32 v141, v36, v133, s0
	v_add_u32_e32 v142, v34, v41
	v_add_u32_e32 v143, 0, v46
	v_add_u32_e32 v144, v35, v56
	v_add_u32_e32 v145, v34, v57
	v_add_u32_e32 v146, 0, v50
	v_add_u32_e32 v147, v35, v51
	v_add_u32_e32 v148, v54, v133
	v_add_u32_e32 v150, v39, v58
	v_add_u32_e32 v151, v47, v59
	v_add_u32_e32 v152, v39, v61
	v_add_u32_e32 v153, v47, v62
	v_add_u32_e32 v154, v39, v64
	v_add_u32_e32 v155, v47, v65
	v_add_u32_e32 v156, v39, v91
	v_add_u32_e32 v157, v47, v42
	v_add_u32_e32 v159, v92, v44
	v_add_u32_e32 v160, v92, v52
	v_add_u32_e32 v161, v92, v60
	v_add_u32_e32 v162, v92, v63
	v_add_u32_e32 v163, v49, v53
	v_add_u32_e32 v164, v37, v38
	s_branch .LBB0_763

.LBB0_763:
	s_waitcnt vmcnt(4)
	v_lshlrev_b32_e32 v38, 16, v70
	v_and_b32_e32 v39, 0xffff0000, v70
	v_mul_f32_e32 v38, 0xbfb8aa3b, v38
	v_mul_f32_e32 v39, 0xbfb8aa3b, v39
	v_exp_f32_e32 v38, v38
	v_exp_f32_e32 v39, v39
	v_and_b32_e32 v49, 0xffff0000, v73
	v_mul_f32_e32 v49, 0xbfb8aa3b, v49
	v_add_f32_e32 v38, 1.0, v38
	v_add_f32_e32 v39, 1.0, v39
	v_rcp_f32_e32 v38, v38
	v_rcp_f32_e32 v39, v39
	v_exp_f32_e32 v49, v49
	v_mov_b32_e32 v90, 0
	v_add_f32_e32 v49, 1.0, v49
	v_rcp_f32_e32 v49, v49
	s_waitcnt vmcnt(0)
	v_mov_b64_e32 v[34:35], v[236:237]
	v_mov_b64_e32 v[36:37], v[238:239]
	v_pk_add_f32 v[60:61], v[34:35], 1.0 op_sel_hi:[1,0] neg_lo:[1,0] neg_hi:[1,0]
	s_nop 0
	v_pk_fma_f32 v[50:51], v[38:39], v[60:61], v[34:35]
	v_pk_add_f32 v[56:57], v[36:37], 1.0 op_sel_hi:[1,0] neg_lo:[1,0] neg_hi:[1,0]
	v_cmp_gt_f32_e32 vcc, s63, v50
	s_nop 1
	v_cndmask_b32_e64 v38, 0, 32, vcc
	v_ldexp_f32 v38, v50, v38
	v_log_f32_e32 v38, v38
	s_nop 0
	v_mul_f32_e32 v39, 0x3f317217, v38
	v_fma_f32 v39, v38, s61, -v39
	v_fmac_f32_e32 v39, 0x3377d1cf, v38
	v_fmac_f32_e32 v39, 0x3f317217, v38
	v_cmp_lt_f32_e64 s[8:9], |v38|, s55
	s_nop 1
	v_cndmask_b32_e64 v38, v38, v39, s[8:9]
	v_cndmask_b32_e32 v39, 0, v216, vcc
	v_cmp_gt_f32_e32 vcc, s63, v51
	v_sub_f32_e32 v42, v38, v39
	s_nop 0
	v_cndmask_b32_e64 v38, 0, 32, vcc
	v_ldexp_f32 v38, v51, v38
	v_log_f32_e32 v38, v38
	s_nop 0
	v_mul_f32_e32 v39, 0x3f317217, v38
	v_fma_f32 v39, v38, s61, -v39
	v_fmac_f32_e32 v39, 0x3377d1cf, v38
	v_fmac_f32_e32 v39, 0x3f317217, v38
	v_cmp_lt_f32_e64 s[8:9], |v38|, s55
	s_nop 1
	v_cndmask_b32_e64 v38, v38, v39, s[8:9]
	v_cndmask_b32_e32 v39, 0, v216, vcc
	v_sub_f32_e32 v43, v38, v39
	v_lshlrev_b32_e32 v38, 16, v71
	v_and_b32_e32 v39, 0xffff0000, v71
	v_mul_f32_e32 v38, 0xbfb8aa3b, v38
	v_mul_f32_e32 v39, 0xbfb8aa3b, v39
	v_exp_f32_e32 v38, v38
	v_exp_f32_e32 v39, v39
	v_add_f32_e32 v38, 1.0, v38
	v_add_f32_e32 v39, 1.0, v39
	v_rcp_f32_e32 v38, v38
	v_rcp_f32_e32 v39, v39
	s_nop 0
	v_pk_fma_f32 v[52:53], v[38:39], v[56:57], v[36:37]
	s_nop 0
	v_cmp_gt_f32_e32 vcc, s63, v52
	s_nop 1
	v_cndmask_b32_e64 v38, 0, 32, vcc
	v_ldexp_f32 v38, v52, v38
	v_log_f32_e32 v38, v38
	s_nop 0
	v_mul_f32_e32 v39, 0x3f317217, v38
	v_fma_f32 v39, v38, s61, -v39
	v_fmac_f32_e32 v39, 0x3377d1cf, v38
	v_fmac_f32_e32 v39, 0x3f317217, v38
	v_cmp_lt_f32_e64 s[8:9], |v38|, s55
	s_nop 1
	v_cndmask_b32_e64 v38, v38, v39, s[8:9]
	v_cndmask_b32_e32 v39, 0, v216, vcc
	v_cmp_gt_f32_e32 vcc, s63, v53
	v_sub_f32_e32 v44, v38, v39
	s_nop 0
	v_cndmask_b32_e64 v38, 0, 32, vcc
	v_ldexp_f32 v38, v53, v38
	v_log_f32_e32 v38, v38
	s_nop 0
	v_mul_f32_e32 v39, 0x3f317217, v38
	v_fma_f32 v39, v38, s61, -v39
	v_fmac_f32_e32 v39, 0x3377d1cf, v38
	v_fmac_f32_e32 v39, 0x3f317217, v38
	v_cmp_lt_f32_e64 s[8:9], |v38|, s55
	s_nop 1
	v_cndmask_b32_e64 v38, v38, v39, s[8:9]
	v_cndmask_b32_e32 v39, 0, v216, vcc
	v_sub_f32_e32 v45, v38, v39
	v_lshlrev_b32_e32 v38, 16, v72
	v_mul_f32_e32 v38, 0xbfb8aa3b, v38
	v_exp_f32_e32 v38, v38
	s_nop 0
	v_add_f32_e32 v38, 1.0, v38
	v_rcp_f32_e32 v46, v38
	v_and_b32_e32 v38, 0xffff0000, v72
	v_mul_f32_e32 v38, 0xbfb8aa3b, v38
	v_exp_f32_e32 v38, v38
	s_nop 0
	v_add_f32_e32 v38, 1.0, v38
	v_rcp_f32_e32 v47, v38
	s_waitcnt vmcnt(0)
	v_mov_b64_e32 v[38:39], v[240:241]
	v_mov_b64_e32 v[40:41], v[242:243]
	v_pk_add_f32 v[62:63], v[38:39], 1.0 op_sel_hi:[1,0] neg_lo:[1,0] neg_hi:[1,0]
	s_nop 0
	v_pk_fma_f32 v[54:55], v[46:47], v[62:63], v[38:39]
	v_pk_add_f32 v[64:65], v[40:41], 1.0 op_sel_hi:[1,0] neg_lo:[1,0] neg_hi:[1,0]
	v_cmp_gt_f32_e32 vcc, s63, v54
	s_nop 1
	v_cndmask_b32_e64 v46, 0, 32, vcc
	v_ldexp_f32 v46, v54, v46
	v_log_f32_e32 v46, v46
	s_nop 0
	v_mul_f32_e32 v47, 0x3f317217, v46
	v_fma_f32 v47, v46, s61, -v47
	v_fmac_f32_e32 v47, 0x3377d1cf, v46
	v_fmac_f32_e32 v47, 0x3f317217, v46
	v_cmp_lt_f32_e64 s[8:9], |v46|, s55
	s_nop 1
	v_cndmask_b32_e64 v46, v46, v47, s[8:9]
	v_cndmask_b32_e32 v47, 0, v216, vcc
	v_cmp_gt_f32_e32 vcc, s63, v55
	v_sub_f32_e32 v46, v46, v47
	s_nop 0
	v_cndmask_b32_e64 v47, 0, 32, vcc
	v_ldexp_f32 v47, v55, v47
	v_log_f32_e32 v47, v47
	s_nop 0
	v_mul_f32_e32 v48, 0x3f317217, v47
	v_fma_f32 v48, v47, s61, -v48
	v_fmac_f32_e32 v48, 0x3377d1cf, v47
	v_fmac_f32_e32 v48, 0x3f317217, v47
	v_cmp_lt_f32_e64 s[8:9], |v47|, s55
	s_nop 1
	v_cndmask_b32_e64 v47, v47, v48, s[8:9]
	v_cndmask_b32_e32 v48, 0, v216, vcc
	v_sub_f32_e32 v47, v47, v48
	v_lshlrev_b32_e32 v48, 16, v73
	v_mul_f32_e32 v48, 0xbfb8aa3b, v48
	v_exp_f32_e32 v48, v48
	s_nop 0
	v_add_f32_e32 v48, 1.0, v48
	v_rcp_f32_e32 v48, v48
	s_nop 0
	v_pk_fma_f32 v[58:59], v[48:49], v[64:65], v[40:41]
	s_nop 0
	v_cmp_gt_f32_e32 vcc, s63, v58
	s_nop 1
	v_cndmask_b32_e64 v48, 0, 32, vcc
	v_ldexp_f32 v48, v58, v48
	v_log_f32_e32 v48, v48
	s_nop 0
	v_mul_f32_e32 v49, 0x3f317217, v48
	v_fma_f32 v49, v48, s61, -v49
	v_fmac_f32_e32 v49, 0x3377d1cf, v48
	v_fmac_f32_e32 v49, 0x3f317217, v48
	v_cmp_lt_f32_e64 s[8:9], |v48|, s55
	s_nop 1
	v_cndmask_b32_e64 v48, v48, v49, s[8:9]
	v_cndmask_b32_e32 v49, 0, v216, vcc
	v_cmp_gt_f32_e32 vcc, s63, v59
	v_sub_f32_e32 v48, v48, v49
	s_nop 0
	v_cndmask_b32_e64 v49, 0, 32, vcc
	v_ldexp_f32 v49, v59, v49
	v_log_f32_e32 v49, v49
	s_nop 0
	v_mul_f32_e32 v91, 0x3f317217, v49
	v_fma_f32 v91, v49, s61, -v91
	v_fmac_f32_e32 v91, 0x3377d1cf, v49
	v_fmac_f32_e32 v91, 0x3f317217, v49
	v_cmp_lt_f32_e64 s[8:9], |v49|, s55
	s_nop 1
	v_cndmask_b32_e64 v49, v49, v91, s[8:9]
	v_cndmask_b32_e32 v91, 0, v216, vcc
	v_sub_f32_e32 v49, v49, v91
	ds_write_b128 v139, v[42:45]
	ds_write_b128 v139, v[46:49] offset:16
	v_lshlrev_b32_e32 v42, 16, v82
	v_and_b32_e32 v43, 0xffff0000, v82
	v_mul_f32_e32 v42, 0xbfb8aa3b, v42
	v_mul_f32_e32 v43, 0xbfb8aa3b, v43
	v_exp_f32_e32 v42, v42
	v_exp_f32_e32 v43, v43
	v_and_b32_e32 v45, 0xffff0000, v83
	v_mul_f32_e32 v45, 0xbfb8aa3b, v45
	v_add_f32_e32 v42, 1.0, v42
	v_add_f32_e32 v43, 1.0, v43
	v_rcp_f32_e32 v42, v42
	v_rcp_f32_e32 v43, v43
	v_exp_f32_e32 v45, v45
	v_and_b32_e32 v47, 0xffff0000, v84
	v_mul_f32_e32 v47, 0xbfb8aa3b, v47
	v_pk_fma_f32 v[42:43], v[42:43], v[60:61], v[34:35]
	v_add_f32_e32 v45, 1.0, v45
	v_cmp_gt_f32_e32 vcc, s63, v42
	v_rcp_f32_e32 v45, v45
	v_exp_f32_e32 v47, v47
	v_cndmask_b32_e64 v34, 0, 32, vcc
	v_ldexp_f32 v34, v42, v34
	v_log_f32_e32 v34, v34
	v_add_f32_e32 v47, 1.0, v47
	v_rcp_f32_e32 v47, v47
	v_and_b32_e32 v49, 0xffff0000, v85
	v_mul_f32_e32 v35, 0x3f317217, v34
	v_fma_f32 v35, v34, s61, -v35
	v_fmac_f32_e32 v35, 0x3377d1cf, v34
	v_fmac_f32_e32 v35, 0x3f317217, v34
	v_cmp_lt_f32_e64 s[8:9], |v34|, s55
	v_mul_f32_e32 v49, 0xbfb8aa3b, v49
	v_exp_f32_e32 v49, v49
	v_cndmask_b32_e64 v34, v34, v35, s[8:9]
	v_cndmask_b32_e32 v35, 0, v216, vcc
	v_cmp_gt_f32_e32 vcc, s63, v43
	v_sub_f32_e32 v34, v34, v35
	v_add_f32_e32 v49, 1.0, v49
	v_cndmask_b32_e64 v35, 0, 32, vcc
	v_ldexp_f32 v35, v43, v35
	v_log_f32_e32 v35, v35
	v_rcp_f32_e32 v49, v49
	v_mul_f32_e32 v44, 0x3f317217, v35
	v_fma_f32 v44, v35, s61, -v44
	v_fmac_f32_e32 v44, 0x3377d1cf, v35
	v_fmac_f32_e32 v44, 0x3f317217, v35
	v_cmp_lt_f32_e64 s[8:9], |v35|, s55
	s_nop 1
	v_cndmask_b32_e64 v35, v35, v44, s[8:9]
	v_cndmask_b32_e32 v44, 0, v216, vcc
	v_sub_f32_e32 v35, v35, v44
	v_lshlrev_b32_e32 v44, 16, v83
	v_mul_f32_e32 v44, 0xbfb8aa3b, v44
	v_exp_f32_e32 v44, v44
	s_nop 0
	v_add_f32_e32 v44, 1.0, v44
	v_rcp_f32_e32 v44, v44
	s_nop 0
	v_pk_fma_f32 v[44:45], v[44:45], v[56:57], v[36:37]
	s_nop 0
	v_cmp_gt_f32_e32 vcc, s63, v44
	s_nop 1
	v_cndmask_b32_e64 v36, 0, 32, vcc
	v_ldexp_f32 v36, v44, v36
	v_log_f32_e32 v36, v36
	s_nop 0
	v_mul_f32_e32 v37, 0x3f317217, v36
	v_fma_f32 v37, v36, s61, -v37
	v_fmac_f32_e32 v37, 0x3377d1cf, v36
	v_fmac_f32_e32 v37, 0x3f317217, v36
	v_cmp_lt_f32_e64 s[8:9], |v36|, s55
	s_nop 1
	v_cndmask_b32_e64 v36, v36, v37, s[8:9]
	v_cndmask_b32_e32 v37, 0, v216, vcc
	v_cmp_gt_f32_e32 vcc, s63, v45
	v_sub_f32_e32 v36, v36, v37
	s_nop 0
	v_cndmask_b32_e64 v37, 0, 32, vcc
	v_ldexp_f32 v37, v45, v37
	v_log_f32_e32 v37, v37
	s_nop 0
	v_mul_f32_e32 v46, 0x3f317217, v37
	v_fma_f32 v46, v37, s61, -v46
	v_fmac_f32_e32 v46, 0x3377d1cf, v37
	v_fmac_f32_e32 v46, 0x3f317217, v37
	v_cmp_lt_f32_e64 s[8:9], |v37|, s55
	s_nop 1
	v_cndmask_b32_e64 v37, v37, v46, s[8:9]
	v_cndmask_b32_e32 v46, 0, v216, vcc
	v_sub_f32_e32 v37, v37, v46
	v_lshlrev_b32_e32 v46, 16, v84
	v_mul_f32_e32 v46, 0xbfb8aa3b, v46
	v_exp_f32_e32 v46, v46
	s_nop 0
	v_add_f32_e32 v46, 1.0, v46
	v_rcp_f32_e32 v46, v46
	s_nop 0
	v_pk_fma_f32 v[38:39], v[46:47], v[62:63], v[38:39]
	s_nop 0
	v_cmp_gt_f32_e32 vcc, s63, v38
	s_nop 1
	v_cndmask_b32_e64 v46, 0, 32, vcc
	v_ldexp_f32 v46, v38, v46
	v_log_f32_e32 v46, v46
	s_nop 0
	v_mul_f32_e32 v47, 0x3f317217, v46
	v_fma_f32 v47, v46, s61, -v47
	v_fmac_f32_e32 v47, 0x3377d1cf, v46
	v_fmac_f32_e32 v47, 0x3f317217, v46
	v_cmp_lt_f32_e64 s[8:9], |v46|, s55
	s_nop 1
	v_cndmask_b32_e64 v46, v46, v47, s[8:9]
	v_cndmask_b32_e32 v47, 0, v216, vcc
	v_cmp_gt_f32_e32 vcc, s63, v39
	v_sub_f32_e32 v46, v46, v47
	s_nop 0
	v_cndmask_b32_e64 v47, 0, 32, vcc
	v_ldexp_f32 v47, v39, v47
	v_log_f32_e32 v47, v47
	s_nop 0
	v_mul_f32_e32 v48, 0x3f317217, v47
	v_fma_f32 v48, v47, s61, -v48
	v_fmac_f32_e32 v48, 0x3377d1cf, v47
	v_fmac_f32_e32 v48, 0x3f317217, v47
	v_cmp_lt_f32_e64 s[8:9], |v47|, s55
	s_nop 1
	v_cndmask_b32_e64 v47, v47, v48, s[8:9]
	v_cndmask_b32_e32 v48, 0, v216, vcc
	v_sub_f32_e32 v47, v47, v48
	v_lshlrev_b32_e32 v48, 16, v85
	v_mul_f32_e32 v48, 0xbfb8aa3b, v48
	v_exp_f32_e32 v48, v48
	s_nop 0
	v_add_f32_e32 v48, 1.0, v48
	v_rcp_f32_e32 v48, v48
	s_nop 0
	v_pk_fma_f32 v[40:41], v[48:49], v[64:65], v[40:41]
	s_nop 0
	v_cmp_gt_f32_e32 vcc, s63, v40
	s_nop 1
	v_cndmask_b32_e64 v48, 0, 32, vcc
	v_ldexp_f32 v48, v40, v48
	v_log_f32_e32 v48, v48
	s_nop 0
	v_mul_f32_e32 v49, 0x3f317217, v48
	v_fma_f32 v49, v48, s61, -v49
	v_fmac_f32_e32 v49, 0x3377d1cf, v48
	v_fmac_f32_e32 v49, 0x3f317217, v48
	v_cmp_lt_f32_e64 s[8:9], |v48|, s55
	s_nop 1
	v_cndmask_b32_e64 v48, v48, v49, s[8:9]
	v_cndmask_b32_e32 v49, 0, v216, vcc
	v_cmp_gt_f32_e32 vcc, s63, v41
	v_sub_f32_e32 v48, v48, v49
	s_nop 0
	v_cndmask_b32_e64 v49, 0, 32, vcc
	v_ldexp_f32 v49, v41, v49
	v_log_f32_e32 v49, v49
	s_nop 0
	v_mul_f32_e32 v56, 0x3f317217, v49
	v_fma_f32 v56, v49, s61, -v56
	v_fmac_f32_e32 v56, 0x3377d1cf, v49
	v_fmac_f32_e32 v56, 0x3f317217, v49
	v_cmp_lt_f32_e64 s[8:9], |v49|, s55
	s_nop 1
	v_cndmask_b32_e64 v49, v49, v56, s[8:9]
	v_cndmask_b32_e32 v56, 0, v216, vcc
	v_sub_f32_e32 v49, v49, v56
	ds_write_b128 v139, v[34:37] offset:16384
	ds_write_b128 v139, v[46:49] offset:16400
	s_waitcnt lgkmcnt(0)
	s_barrier
	ds_read2st64_b32 v[34:35], v164 offset1:2
	s_waitcnt lgkmcnt(0)
	v_add_f32_e32 v34, 0, v34
	v_add_f32_e32 v36, v34, v35
	ds_write2st64_b32 v164, v34, v36 offset1:2
	ds_read2st64_b32 v[34:35], v164 offset0:4 offset1:6
	s_waitcnt lgkmcnt(0)
	v_add_f32_e32 v34, v36, v34
	v_add_f32_e32 v36, v34, v35
	ds_write2st64_b32 v164, v34, v36 offset0:4 offset1:6
	ds_read2st64_b32 v[34:35], v164 offset0:8 offset1:10
	s_waitcnt lgkmcnt(0)
	v_add_f32_e32 v34, v36, v34
	v_add_f32_e32 v36, v34, v35
	ds_write2st64_b32 v164, v34, v36 offset0:8 offset1:10
	ds_read2st64_b32 v[34:35], v164 offset0:12 offset1:14
	s_waitcnt lgkmcnt(0)
	v_add_f32_e32 v34, v36, v34
	v_add_f32_e32 v36, v34, v35
	ds_write2st64_b32 v164, v34, v36 offset0:12 offset1:14
	ds_read2st64_b32 v[34:35], v164 offset0:16 offset1:18
	s_waitcnt lgkmcnt(0)
	v_add_f32_e32 v34, v36, v34
	v_add_f32_e32 v36, v34, v35
	ds_write2st64_b32 v164, v34, v36 offset0:16 offset1:18
	ds_read2st64_b32 v[34:35], v164 offset0:20 offset1:22
	s_waitcnt lgkmcnt(0)
	v_add_f32_e32 v34, v36, v34
	v_add_f32_e32 v36, v34, v35
	ds_write2st64_b32 v164, v34, v36 offset0:20 offset1:22
	ds_read2st64_b32 v[34:35], v164 offset0:24 offset1:26
	s_waitcnt lgkmcnt(0)
	v_add_f32_e32 v34, v36, v34
	v_add_f32_e32 v36, v34, v35
	ds_write2st64_b32 v164, v34, v36 offset0:24 offset1:26
	ds_read2st64_b32 v[34:35], v164 offset0:28 offset1:30
	s_waitcnt lgkmcnt(0)
	v_add_f32_e32 v36, v36, v34
	v_add_f32_e32 v34, v36, v35
	ds_write2st64_b32 v164, v36, v34 offset0:28 offset1:30
	ds_write_b32 v131, v34
	s_waitcnt lgkmcnt(0)
	s_barrier
	s_and_saveexec_b64 s[0:1], s[6:7]
	s_cbranch_execz .LBB0_774
	v_mov_b32_e32 v90, 0
	s_mov_b64 s[8:9], 0
	v_mov_b32_e32 v35, v0
	v_mov_b32_e32 v36, v130

.LBB0_776:
	v_mov_b32_e32 v44, v212
	s_waitcnt lgkmcnt(0)
	s_barrier
	s_xor_b32 s8, s18, 63
	v_readfirstlane_b32 s1, v44
	s_ashr_i32 s0, s1, 6
	v_readlane_b32 s2, v253, 46
	s_add_u32 s4, s2, s14
	v_readlane_b32 s2, v253, 47
	s_addc_u32 s5, s2, s15
	s_lshl_b32 s2, s8, 4
	s_add_u32 s2, s2, s19
	s_addc_u32 s3, 0, s20
	s_lshl_b64 s[2:3], s[2:3], 16
	v_readlane_b32 s6, v253, 48
	s_add_u32 s6, s6, s2
	v_readlane_b32 s2, v253, 49
	v_bfe_u32 v46, v44, 5, 1
	s_addc_u32 s7, s2, s3
	s_ashr_i32 s2, s1, 7
	v_and_b32_e32 v45, 31, v44
	s_lshl_b32 s9, s2, 12
	v_lshlrev_b32_e32 v0, 9, v46
	s_and_b32 s3, s1, 64
	v_or3_b32 v0, v0, s9, v45
	v_or_b32_e32 v16, s3, v0
	v_ashrrev_i32_e32 v17, 31, v16
	v_lshl_add_u64 v[8:9], v[16:17], 2, s[6:7]
	s_movk_i32 s9, 0x1000
	v_add_co_u32_e32 v14, vcc, s9, v8
	s_movk_i32 s13, 0x3000
	s_nop 0
	v_addc_co_u32_e32 v15, vcc, 0, v9, vcc
	v_add_co_u32_e32 v18, vcc, s33, v8
	global_load_dword v2, v[8:9], off
	global_load_dword v3, v[8:9], off offset:512
	global_load_dword v4, v[8:9], off offset:1024
	global_load_dword v5, v[8:9], off offset:1536
	v_addc_co_u32_e32 v19, vcc, 0, v9, vcc
	global_load_dword v6, v[18:19], off offset:-4096
	global_load_dword v10, v[18:19], off
	global_load_dword v11, v[18:19], off offset:512
	global_load_dword v12, v[18:19], off offset:1024
	global_load_dword v13, v[18:19], off offset:1536
	v_add_co_u32_e32 v18, vcc, s13, v8
	v_ashrrev_i32_e32 v17, 31, v0
	s_nop 0
	v_addc_co_u32_e32 v19, vcc, 0, v9, vcc
	v_lshl_add_u64 v[30:31], v[16:17], 2, s[6:7]
	global_load_dword v7, v[14:15], off offset:512
	global_load_dword v8, v[14:15], off offset:1024
	global_load_dword v9, v[14:15], off offset:1536
	s_nop 0
	global_load_dword v14, v[18:19], off
	v_add_co_u32_e32 v26, vcc, s9, v30
	s_lshl_b32 s6, s8, 8
	s_nop 0
	v_addc_co_u32_e32 v27, vcc, 0, v31, vcc
	global_load_dword v15, v[18:19], off offset:512
	global_load_dword v16, v[18:19], off offset:1024
	global_load_dword v17, v[18:19], off offset:1536
	s_nop 0
	global_load_dword v18, v[30:31], off offset:128
	global_load_dword v19, v[30:31], off offset:640
	global_load_dword v20, v[30:31], off offset:1152
	global_load_dword v21, v[30:31], off offset:1664
	global_load_dword v22, v[26:27], off offset:128
	v_add_co_u32_e32 v32, vcc, s33, v30
	s_xor_b32 s18, s6, 0x3f00
	s_nop 0
	v_addc_co_u32_e32 v33, vcc, 0, v31, vcc
	global_load_dword v23, v[26:27], off offset:640
	global_load_dword v24, v[26:27], off offset:1152
	global_load_dword v25, v[26:27], off offset:1664
	s_nop 0
	global_load_dword v26, v[32:33], off offset:128
	global_load_dword v27, v[32:33], off offset:640
	global_load_dword v28, v[32:33], off offset:1152
	global_load_dword v29, v[32:33], off offset:1664
	v_add_co_u32_e32 v34, vcc, s13, v30
	s_lshl_b32 s6, s2, 6
	s_nop 0
	v_addc_co_u32_e32 v35, vcc, 0, v31, vcc
	global_load_dword v30, v[34:35], off offset:128
	global_load_dword v31, v[34:35], off offset:640
	global_load_dword v32, v[34:35], off offset:1152
	global_load_dword v33, v[34:35], off offset:1664
	v_readlane_b32 s17, v255, 5
	v_lshlrev_b32_e32 v34, 3, v46
	v_or_b32_e32 v48, s3, v45
	s_add_i32 s3, s17, s6
	v_add_u32_e32 v52, 0x200, v44
	v_add_u32_e32 v50, s3, v34
	s_or_b32 s3, s18, 0xc0
	v_ashrrev_i32_e32 v132, 4, v52
	v_lshlrev_b32_e32 v35, 3, v44
	v_add_u32_e32 v38, s3, v132
	v_and_b32_e32 v51, 0x78, v35
	v_ashrrev_i32_e32 v39, 31, v38
	v_or_b32_e32 v130, s10, v51
	v_mov_b32_e32 v131, s11
	v_lshlrev_b64 v[38:39], 10, v[38:39]
	v_lshl_add_u64 v[38:39], v[38:39], 0, v[130:131]
	v_lshlrev_b64 v[38:39], 1, v[38:39]
	s_movk_i32 s27, 0x110
	v_lshl_add_u64 v[40:41], s[86:87], 0, v[38:39]
	v_mad_u32_u24 v0, v48, s27, v50
	global_load_dwordx4 v[66:69], v[40:41], off
	v_or_b32_e32 v53, 32, v48
	v_ashrrev_i32_e32 v134, 4, v44
	s_lshl_b64 s[14:15], s[10:11], 1
	v_lshlrev_b32_e32 v35, 2, v44
	v_readlane_b32 s6, v253, 45
	v_readlane_b32 s7, v255, 7
	v_readlane_b32 s10, v255, 4
	v_readlane_b32 s16, v255, 3
	v_lshl_add_u32 v162, v45, 2, s7
	v_readlane_b32 s26, v255, 2
	s_movk_i32 s25, 0x90
	v_lshrrev_b32_e32 v56, 7, v44
	v_add_u32_e32 v159, s26, v35
	v_lshrrev_b32_e32 v52, 7, v52
	v_xor_b32_e32 v56, v56, v44
	v_xor_b32_e32 v52, v52, v44
	v_lshlrev_b32_e32 v56, 4, v56
	v_lshlrev_b32_e32 v57, 1, v134
	v_lshlrev_b32_e32 v52, 4, v52
	v_lshlrev_b32_e32 v58, 1, v132
	v_lshl_add_u32 v161, v51, 1, 0
	v_and_b32_e32 v56, 0x70, v56
	v_and_b32_e32 v57, 14, v57
	v_and_b32_e32 v52, 0x70, v52
	v_and_b32_e32 v58, 14, v58
	v_or_b32_e32 v60, 2, v46
	v_or_b32_e32 v63, 4, v46
	v_or_b32_e32 v90, 6, v46
	s_waitcnt vmcnt(31)
	v_cvt_pk_bf16_f32 v36, v2, v3
	v_and_b32_e32 v47, 63, v44
	s_waitcnt vmcnt(29)
	v_cvt_pk_bf16_f32 v37, v4, v5
	v_ashrrev_i32_e32 v158, 7, v44
	v_mul_u32_u24_e32 v54, 0x110, v53
	v_lshlrev_b32_e32 v138, 4, v46
	v_lshl_add_u32 v168, s0, 7, v162
	v_mad_u32_u24 v92, v53, s25, 0
	v_mov_b32_e32 v139, v1
	s_waitcnt vmcnt(23)
	v_cvt_pk_bf16_f32 v40, v6, v7
	v_ashrrev_i32_e32 v133, 31, v132
	s_waitcnt vmcnt(21)
	v_cvt_pk_bf16_f32 v41, v8, v9
	ds_write2_b64 v0, v[36:37], v[40:41] offset1:2
	v_cvt_pk_bf16_f32 v36, v10, v11
	v_cvt_pk_bf16_f32 v37, v12, v13
	s_waitcnt vmcnt(19)
	v_cvt_pk_bf16_f32 v40, v14, v15
	s_waitcnt vmcnt(17)
	v_cvt_pk_bf16_f32 v41, v16, v17
	ds_write2_b64 v0, v[36:37], v[40:41] offset0:4 offset1:6
	v_mad_u32_u24 v0, v53, s27, v50
	s_waitcnt vmcnt(15)
	v_cvt_pk_bf16_f32 v36, v18, v19
	s_waitcnt vmcnt(13)
	v_cvt_pk_bf16_f32 v37, v20, v21
	s_waitcnt vmcnt(11)
	v_cvt_pk_bf16_f32 v40, v22, v23
	s_waitcnt vmcnt(9)
	v_cvt_pk_bf16_f32 v41, v24, v25
	ds_write2_b64 v0, v[36:37], v[40:41] offset1:2
	v_add_u32_e32 v40, s3, v134
	v_ashrrev_i32_e32 v41, 31, v40
	v_lshlrev_b64 v[40:41], 10, v[40:41]
	v_lshl_add_u64 v[40:41], v[40:41], 0, v[130:131]
	v_lshlrev_b64 v[40:41], 1, v[40:41]
	v_lshl_add_u64 v[42:43], s[90:91], 0, v[40:41]
	s_waitcnt vmcnt(7)
	v_cvt_pk_bf16_f32 v36, v26, v27
	s_waitcnt vmcnt(5)
	v_cvt_pk_bf16_f32 v37, v28, v29
	global_load_dwordx4 v[70:73], v[42:43], off
	s_waitcnt vmcnt(4)
	v_cvt_pk_bf16_f32 v42, v30, v31
	s_waitcnt vmcnt(2)
	v_cvt_pk_bf16_f32 v43, v32, v33
	ds_write2_b64 v0, v[36:37], v[42:43] offset0:4 offset1:6
	v_lshl_add_u64 v[36:37], s[76:77], 0, v[40:41]
	v_lshl_add_u64 v[40:41], s[86:87], 0, v[40:41]
	global_load_dwordx4 v[74:77], v[36:37], off
	global_load_dwordx4 v[78:81], v[40:41], off
	v_lshl_add_u64 v[36:37], s[90:91], 0, v[38:39]
	v_lshl_add_u64 v[38:39], s[76:77], 0, v[38:39]
	global_load_dwordx4 v[82:85], v[36:37], off
	global_load_dwordx4 v[86:89], v[38:39], off
	v_readlane_b32 s3, v253, 44
	s_add_u32 s3, s3, s14
	v_and_b32_e32 v37, 0x1fc, v35
	s_addc_u32 s6, s6, s15
	s_and_b32 s7, s1, 0xffffff80
	s_add_i32 s19, s10, s7
	v_add_u32_e32 v163, s10, v37
	s_ashr_i32 s10, s1, 8
	s_lshl_b32 s1, s0, 5
	v_lshlrev_b32_e32 v0, 2, v51
	s_and_b32 s24, s1, 0x60
	v_lshl_add_u64 v[136:137], s[4:5], 0, v[0:1]
	global_load_dwordx4 v[236:239], v[136:137], off
	global_load_dwordx4 v[240:243], v[136:137], off offset:16
	v_add_u32_e32 v36, s21, v0
	v_add_u32_e32 v160, s16, v0
	v_lshl_or_b32 v0, s2, 5, v45
	s_lshl_b32 s11, s10, 5
	s_lshl_b32 s1, s24, 1
	v_mul_lo_u32 v35, v0, s25
	s_add_u32 s2, s3, s1
	v_add_u32_e32 v39, 0, v35
	s_addc_u32 s3, s6, 0
	v_mov_b32_e32 v35, v1
	v_or_b32_e32 v165, s11, v45
	v_lshl_add_u64 v[140:141], s[2:3], 0, v[34:35]
	v_or_b32_e32 v35, s24, v45
	v_mov_b32_e32 v41, s17
	v_lshrrev_b32_e32 v0, 3, v0
	s_ashr_i32 s1, s0, 31
	v_mad_u32_u24 v41, v35, s27, v41
	v_mul_lo_u32 v42, v165, s27
	v_bfe_u32 v166, v35, 3, 3
	v_mul_u32_u24_e32 v35, 0x90, v35
	v_mul_u32_u24_e32 v51, 0x90, v51
	s_lshl_b64 s[2:3], s[0:1], 13
	v_add_u32_e32 v43, 0, v42
	v_add3_u32 v167, 0, v35, v34
	v_add_u32_e32 v35, s21, v42
	v_and_b32_e32 v34, 15, v44
	v_lshlrev_b32_e32 v42, 5, v44
	v_or3_b32 v56, v56, v57, v51
	v_or3_b32 v51, v52, v58, v51
	v_bfe_u32 v44, v44, 3, 2
	v_bitop3_b32 v58, v0, v46, 7 bitop3:0x6c
	v_bitop3_b32 v61, v0, v60, 7 bitop3:0x6c
	v_bitop3_b32 v64, v0, v63, 7 bitop3:0x6c
	v_bitop3_b32 v0, v0, v90, 7 bitop3:0x6c
	s_cmp_lt_i32 s10, 2
	v_lshlrev_b32_e32 v91, 4, v0
	v_bitop3_b32 v0, v46, v44, 6 bitop3:0x36
	v_add_u32_e32 v164, s16, v37
	s_cselect_b64 s[16:17], -1, 0
	s_lshl_b32 s20, s10, 9
	v_xor_b32_e32 v59, v46, v44
	v_bitop3_b32 v62, v46, v44, 2 bitop3:0x36
	v_bitop3_b32 v65, v46, v44, 4 bitop3:0x36
	v_lshlrev_b32_e32 v44, 4, v0
	v_lshrrev_b32_e32 v0, 3, v53
	v_lshlrev_b32_e32 v40, 2, v46
	v_bitop3_b32 v46, v0, v46, 7 bitop3:0x6c
	v_bitop3_b32 v53, v0, v60, 7 bitop3:0x6c
	v_bitop3_b32 v60, v0, v63, 7 bitop3:0x6c
	v_bitop3_b32 v0, v0, v90, 7 bitop3:0x6c
	s_add_u32 s0, s22, s2
	v_lshlrev_b32_e32 v63, 4, v0
	s_addc_u32 s1, s23, s3
	v_lshlrev_b32_e32 v0, 4, v47
	v_cmp_gt_u32_e64 s[6:7], 32, v47
	v_lshl_add_u64 v[146:147], s[0:1], 0, v[0:1]
	v_and_b32_e32 v47, 64, v215
	s_lshl_b32 s0, s24, 2
	v_readlane_b32 s2, v254, 48
	v_xor_b32_e32 v0, 32, v215
	v_add_u32_e32 v47, 64, v47
	v_readlane_b32 s3, v254, 49
	s_add_u32 s0, s2, s0
	v_cmp_lt_i32_e32 vcc, v0, v47
	s_addc_u32 s1, s3, 0
	v_and_b32_e32 v42, 0xfffffe00, v42
	v_cndmask_b32_e32 v0, v215, v0, vcc
	v_lshl_add_u64 v[148:149], s[0:1], 0, v[138:139]
	s_mul_i32 s0, s10, 0x2200
	v_add_u32_e32 v170, v36, v42
	v_lshlrev_b32_e32 v42, 13, v158
	v_or_b32_e32 v52, s24, v40
	v_lshlrev_b64 v[144:145], 12, v[132:133]
	v_lshlrev_b32_e32 v133, 2, v0
	v_mov_b32_e32 v0, s0
	v_mul_u32_u24_e32 v49, 0x110, v48
	v_add_u32_e32 v38, s21, v37
	v_lshl_add_u32 v169, v34, 4, s21
	v_lshlrev_b32_e32 v34, 3, v34
	v_sub_u32_e32 v42, 0, v42
	v_lshlrev_b32_e32 v55, 9, v134
	v_lshlrev_b32_e32 v57, 9, v132
	v_lshlrev_b32_e32 v52, 1, v52
	v_ashrrev_i32_e32 v135, 31, v134
	v_mad_u32_u24 v48, v48, s25, 0
	v_lshlrev_b32_e32 v58, 4, v58
	v_lshlrev_b32_e32 v59, 4, v59
	v_lshlrev_b32_e32 v61, 4, v61
	v_lshlrev_b32_e32 v62, 4, v62
	v_lshlrev_b32_e32 v64, 4, v64
	v_lshlrev_b32_e32 v65, 4, v65
	v_lshlrev_b32_e32 v46, 4, v46
	v_lshlrev_b32_e32 v53, 4, v53
	v_lshlrev_b32_e32 v60, 4, v60
	v_mad_u32_u24 v0, v45, s27, v0
	v_readlane_b32 s0, v255, 6
	s_mov_b32 s13, 0
	v_cmp_lt_i32_e64 s[8:9], 0, v158
	v_cmp_eq_u32_e64 s[4:5], 3, v158
	v_mul_lo_u32 v171, v134, s27
	v_mul_lo_u32 v172, v132, s27
	v_lshlrev_b64 v[142:143], 12, v[134:135]
	v_add_u32_e32 v135, s26, v37
	s_add_i32 s21, s10, -1
	s_lshl_b32 s22, s10, 2
	v_add3_u32 v139, v0, v138, s0
	v_or3_b32 v173, v40, s11, 27
	v_add_u32_e32 v174, v36, v55
	v_add_u32_e32 v175, 0, v56
	v_add_u32_e32 v188, v36, v57
	v_add_u32_e32 v189, 0, v51
	v_add_u32_e32 v190, v41, v138
	v_add_u32_e32 v191, v43, v138
	v_add_u32_e32 v192, v35, v52
	v_lshlrev_b32_e32 v0, 1, v34
	v_add_u32_e32 v193, v39, v58
	v_add_u32_e32 v194, v48, v59
	v_add_u32_e32 v195, v39, v61
	v_add_u32_e32 v196, v48, v62
	v_add_u32_e32 v197, v39, v64
	v_add_u32_e32 v198, v48, v65
	v_add_u32_e32 v199, v39, v91
	v_add_u32_e32 v200, v48, v44
	v_add_u32_e32 v201, v50, v49
	v_add_u32_e32 v202, v92, v46
	v_add_u32_e32 v203, v92, v53
	v_add_u32_e32 v204, v92, v60
	v_add_u32_e32 v205, v92, v63
	v_add_u32_e32 v206, v50, v54
	v_add_u32_e32 v207, v38, v42
	s_branch .LBB0_778

.LBB0_778:
	s_waitcnt vmcnt(4)
	v_lshlrev_b32_e32 v38, 16, v70
	v_and_b32_e32 v39, 0xffff0000, v70
	v_mul_f32_e32 v38, 0xbfb8aa3b, v38
	v_mul_f32_e32 v39, 0xbfb8aa3b, v39
	v_exp_f32_e32 v38, v38
	v_exp_f32_e32 v39, v39
	v_and_b32_e32 v49, 0xffff0000, v73
	v_mul_f32_e32 v49, 0xbfb8aa3b, v49
	v_add_f32_e32 v38, 1.0, v38
	v_add_f32_e32 v39, 1.0, v39
	v_rcp_f32_e32 v38, v38
	v_rcp_f32_e32 v39, v39
	v_exp_f32_e32 v49, v49
	v_mov_b32_e32 v90, 0
	v_add_f32_e32 v49, 1.0, v49
	v_rcp_f32_e32 v49, v49
	s_waitcnt vmcnt(0)
	v_mov_b64_e32 v[34:35], v[236:237]
	v_mov_b64_e32 v[36:37], v[238:239]
	v_pk_add_f32 v[60:61], v[34:35], 1.0 op_sel_hi:[1,0] neg_lo:[1,0] neg_hi:[1,0]
	s_nop 0
	v_pk_fma_f32 v[50:51], v[38:39], v[60:61], v[34:35]
	v_pk_add_f32 v[56:57], v[36:37], 1.0 op_sel_hi:[1,0] neg_lo:[1,0] neg_hi:[1,0]
	v_cmp_gt_f32_e32 vcc, s63, v50
	s_nop 1
	v_cndmask_b32_e64 v38, 0, 32, vcc
	v_ldexp_f32 v38, v50, v38
	v_log_f32_e32 v38, v38
	s_nop 0
	v_mul_f32_e32 v39, 0x3f317217, v38
	v_fma_f32 v39, v38, s61, -v39
	v_fmac_f32_e32 v39, 0x3377d1cf, v38
	v_fmac_f32_e32 v39, 0x3f317217, v38
	v_cmp_lt_f32_e64 s[10:11], |v38|, s55
	s_nop 1
	v_cndmask_b32_e64 v38, v38, v39, s[10:11]
	v_cndmask_b32_e32 v39, 0, v216, vcc
	v_cmp_gt_f32_e32 vcc, s63, v51
	v_sub_f32_e32 v42, v38, v39
	s_nop 0
	v_cndmask_b32_e64 v38, 0, 32, vcc
	v_ldexp_f32 v38, v51, v38
	v_log_f32_e32 v38, v38
	s_nop 0
	v_mul_f32_e32 v39, 0x3f317217, v38
	v_fma_f32 v39, v38, s61, -v39
	v_fmac_f32_e32 v39, 0x3377d1cf, v38
	v_fmac_f32_e32 v39, 0x3f317217, v38
	v_cmp_lt_f32_e64 s[10:11], |v38|, s55
	s_nop 1
	v_cndmask_b32_e64 v38, v38, v39, s[10:11]
	v_cndmask_b32_e32 v39, 0, v216, vcc
	v_sub_f32_e32 v43, v38, v39
	v_lshlrev_b32_e32 v38, 16, v71
	v_and_b32_e32 v39, 0xffff0000, v71
	v_mul_f32_e32 v38, 0xbfb8aa3b, v38
	v_mul_f32_e32 v39, 0xbfb8aa3b, v39
	v_exp_f32_e32 v38, v38
	v_exp_f32_e32 v39, v39
	v_add_f32_e32 v38, 1.0, v38
	v_add_f32_e32 v39, 1.0, v39
	v_rcp_f32_e32 v38, v38
	v_rcp_f32_e32 v39, v39
	s_nop 0
	v_pk_fma_f32 v[52:53], v[38:39], v[56:57], v[36:37]
	s_nop 0
	v_cmp_gt_f32_e32 vcc, s63, v52
	s_nop 1
	v_cndmask_b32_e64 v38, 0, 32, vcc
	v_ldexp_f32 v38, v52, v38
	v_log_f32_e32 v38, v38
	s_nop 0
	v_mul_f32_e32 v39, 0x3f317217, v38
	v_fma_f32 v39, v38, s61, -v39
	v_fmac_f32_e32 v39, 0x3377d1cf, v38
	v_fmac_f32_e32 v39, 0x3f317217, v38
	v_cmp_lt_f32_e64 s[10:11], |v38|, s55
	s_nop 1
	v_cndmask_b32_e64 v38, v38, v39, s[10:11]
	v_cndmask_b32_e32 v39, 0, v216, vcc
	v_cmp_gt_f32_e32 vcc, s63, v53
	v_sub_f32_e32 v44, v38, v39
	s_nop 0
	v_cndmask_b32_e64 v38, 0, 32, vcc
	v_ldexp_f32 v38, v53, v38
	v_log_f32_e32 v38, v38
	s_nop 0
	v_mul_f32_e32 v39, 0x3f317217, v38
	v_fma_f32 v39, v38, s61, -v39
	v_fmac_f32_e32 v39, 0x3377d1cf, v38
	v_fmac_f32_e32 v39, 0x3f317217, v38
	v_cmp_lt_f32_e64 s[10:11], |v38|, s55
	s_nop 1
	v_cndmask_b32_e64 v38, v38, v39, s[10:11]
	v_cndmask_b32_e32 v39, 0, v216, vcc
	v_sub_f32_e32 v45, v38, v39
	v_lshlrev_b32_e32 v38, 16, v72
	v_mul_f32_e32 v38, 0xbfb8aa3b, v38
	v_exp_f32_e32 v38, v38
	s_nop 0
	v_add_f32_e32 v38, 1.0, v38
	v_rcp_f32_e32 v46, v38
	v_and_b32_e32 v38, 0xffff0000, v72
	v_mul_f32_e32 v38, 0xbfb8aa3b, v38
	v_exp_f32_e32 v38, v38
	s_nop 0
	v_add_f32_e32 v38, 1.0, v38
	v_rcp_f32_e32 v47, v38
	s_waitcnt vmcnt(0)
	v_mov_b64_e32 v[38:39], v[240:241]
	v_mov_b64_e32 v[40:41], v[242:243]
	v_pk_add_f32 v[62:63], v[38:39], 1.0 op_sel_hi:[1,0] neg_lo:[1,0] neg_hi:[1,0]
	s_nop 0
	v_pk_fma_f32 v[54:55], v[46:47], v[62:63], v[38:39]
	v_pk_add_f32 v[64:65], v[40:41], 1.0 op_sel_hi:[1,0] neg_lo:[1,0] neg_hi:[1,0]
	v_cmp_gt_f32_e32 vcc, s63, v54
	s_nop 1
	v_cndmask_b32_e64 v46, 0, 32, vcc
	v_ldexp_f32 v46, v54, v46
	v_log_f32_e32 v46, v46
	s_nop 0
	v_mul_f32_e32 v47, 0x3f317217, v46
	v_fma_f32 v47, v46, s61, -v47
	v_fmac_f32_e32 v47, 0x3377d1cf, v46
	v_fmac_f32_e32 v47, 0x3f317217, v46
	v_cmp_lt_f32_e64 s[10:11], |v46|, s55
	s_nop 1
	v_cndmask_b32_e64 v46, v46, v47, s[10:11]
	v_cndmask_b32_e32 v47, 0, v216, vcc
	v_cmp_gt_f32_e32 vcc, s63, v55
	v_sub_f32_e32 v46, v46, v47
	s_nop 0
	v_cndmask_b32_e64 v47, 0, 32, vcc
	v_ldexp_f32 v47, v55, v47
	v_log_f32_e32 v47, v47
	s_nop 0
	v_mul_f32_e32 v48, 0x3f317217, v47
	v_fma_f32 v48, v47, s61, -v48
	v_fmac_f32_e32 v48, 0x3377d1cf, v47
	v_fmac_f32_e32 v48, 0x3f317217, v47
	v_cmp_lt_f32_e64 s[10:11], |v47|, s55
	s_nop 1
	v_cndmask_b32_e64 v47, v47, v48, s[10:11]
	v_cndmask_b32_e32 v48, 0, v216, vcc
	v_sub_f32_e32 v47, v47, v48
	v_lshlrev_b32_e32 v48, 16, v73
	v_mul_f32_e32 v48, 0xbfb8aa3b, v48
	v_exp_f32_e32 v48, v48
	s_nop 0
	v_add_f32_e32 v48, 1.0, v48
	v_rcp_f32_e32 v48, v48
	s_nop 0
	v_pk_fma_f32 v[58:59], v[48:49], v[64:65], v[40:41]
	s_nop 0
	v_cmp_gt_f32_e32 vcc, s63, v58
	s_nop 1
	v_cndmask_b32_e64 v48, 0, 32, vcc
	v_ldexp_f32 v48, v58, v48
	v_log_f32_e32 v48, v48
	s_nop 0
	v_mul_f32_e32 v49, 0x3f317217, v48
	v_fma_f32 v49, v48, s61, -v49
	v_fmac_f32_e32 v49, 0x3377d1cf, v48
	v_fmac_f32_e32 v49, 0x3f317217, v48
	v_cmp_lt_f32_e64 s[10:11], |v48|, s55
	s_nop 1
	v_cndmask_b32_e64 v48, v48, v49, s[10:11]
	v_cndmask_b32_e32 v49, 0, v216, vcc
	v_cmp_gt_f32_e32 vcc, s63, v59
	v_sub_f32_e32 v48, v48, v49
	s_nop 0
	v_cndmask_b32_e64 v49, 0, 32, vcc
	v_ldexp_f32 v49, v59, v49
	v_log_f32_e32 v49, v49
	s_nop 0
	v_mul_f32_e32 v91, 0x3f317217, v49
	v_fma_f32 v91, v49, s61, -v91
	v_fmac_f32_e32 v91, 0x3377d1cf, v49
	v_fmac_f32_e32 v91, 0x3f317217, v49
	v_cmp_lt_f32_e64 s[10:11], |v49|, s55
	s_nop 1
	v_cndmask_b32_e64 v49, v49, v91, s[10:11]
	v_cndmask_b32_e32 v91, 0, v216, vcc
	v_sub_f32_e32 v49, v49, v91
	ds_write_b128 v170, v[42:45]
	ds_write_b128 v170, v[46:49] offset:16
	v_lshlrev_b32_e32 v42, 16, v82
	v_and_b32_e32 v43, 0xffff0000, v82
	v_mul_f32_e32 v42, 0xbfb8aa3b, v42
	v_mul_f32_e32 v43, 0xbfb8aa3b, v43
	v_exp_f32_e32 v42, v42
	v_exp_f32_e32 v43, v43
	v_and_b32_e32 v45, 0xffff0000, v83
	v_mul_f32_e32 v45, 0xbfb8aa3b, v45
	v_add_f32_e32 v42, 1.0, v42
	v_add_f32_e32 v43, 1.0, v43
	v_rcp_f32_e32 v42, v42
	v_rcp_f32_e32 v43, v43
	v_exp_f32_e32 v45, v45
	v_and_b32_e32 v47, 0xffff0000, v84
	v_mul_f32_e32 v47, 0xbfb8aa3b, v47
	v_pk_fma_f32 v[42:43], v[42:43], v[60:61], v[34:35]
	v_add_f32_e32 v45, 1.0, v45
	v_cmp_gt_f32_e32 vcc, s63, v42
	v_rcp_f32_e32 v45, v45
	v_exp_f32_e32 v47, v47
	v_cndmask_b32_e64 v34, 0, 32, vcc
	v_ldexp_f32 v34, v42, v34
	v_log_f32_e32 v34, v34
	v_add_f32_e32 v47, 1.0, v47
	v_rcp_f32_e32 v47, v47
	v_and_b32_e32 v49, 0xffff0000, v85
	v_mul_f32_e32 v35, 0x3f317217, v34
	v_fma_f32 v35, v34, s61, -v35
	v_fmac_f32_e32 v35, 0x3377d1cf, v34
	v_fmac_f32_e32 v35, 0x3f317217, v34
	v_cmp_lt_f32_e64 s[10:11], |v34|, s55
	v_mul_f32_e32 v49, 0xbfb8aa3b, v49
	v_exp_f32_e32 v49, v49
	v_cndmask_b32_e64 v34, v34, v35, s[10:11]
	v_cndmask_b32_e32 v35, 0, v216, vcc
	v_cmp_gt_f32_e32 vcc, s63, v43
	v_sub_f32_e32 v34, v34, v35
	v_add_f32_e32 v49, 1.0, v49
	v_cndmask_b32_e64 v35, 0, 32, vcc
	v_ldexp_f32 v35, v43, v35
	v_log_f32_e32 v35, v35
	v_rcp_f32_e32 v49, v49
	v_mul_f32_e32 v44, 0x3f317217, v35
	v_fma_f32 v44, v35, s61, -v44
	v_fmac_f32_e32 v44, 0x3377d1cf, v35
	v_fmac_f32_e32 v44, 0x3f317217, v35
	v_cmp_lt_f32_e64 s[10:11], |v35|, s55
	s_nop 1
	v_cndmask_b32_e64 v35, v35, v44, s[10:11]
	v_cndmask_b32_e32 v44, 0, v216, vcc
	v_sub_f32_e32 v35, v35, v44
	v_lshlrev_b32_e32 v44, 16, v83
	v_mul_f32_e32 v44, 0xbfb8aa3b, v44
	v_exp_f32_e32 v44, v44
	s_nop 0
	v_add_f32_e32 v44, 1.0, v44
	v_rcp_f32_e32 v44, v44
	s_nop 0
	v_pk_fma_f32 v[44:45], v[44:45], v[56:57], v[36:37]
	s_nop 0
	v_cmp_gt_f32_e32 vcc, s63, v44
	s_nop 1
	v_cndmask_b32_e64 v36, 0, 32, vcc
	v_ldexp_f32 v36, v44, v36
	v_log_f32_e32 v36, v36
	s_nop 0
	v_mul_f32_e32 v37, 0x3f317217, v36
	v_fma_f32 v37, v36, s61, -v37
	v_fmac_f32_e32 v37, 0x3377d1cf, v36
	v_fmac_f32_e32 v37, 0x3f317217, v36
	v_cmp_lt_f32_e64 s[10:11], |v36|, s55
	s_nop 1
	v_cndmask_b32_e64 v36, v36, v37, s[10:11]
	v_cndmask_b32_e32 v37, 0, v216, vcc
	v_cmp_gt_f32_e32 vcc, s63, v45
	v_sub_f32_e32 v36, v36, v37
	s_nop 0
	v_cndmask_b32_e64 v37, 0, 32, vcc
	v_ldexp_f32 v37, v45, v37
	v_log_f32_e32 v37, v37
	s_nop 0
	v_mul_f32_e32 v46, 0x3f317217, v37
	v_fma_f32 v46, v37, s61, -v46
	v_fmac_f32_e32 v46, 0x3377d1cf, v37
	v_fmac_f32_e32 v46, 0x3f317217, v37
	v_cmp_lt_f32_e64 s[10:11], |v37|, s55
	s_nop 1
	v_cndmask_b32_e64 v37, v37, v46, s[10:11]
	v_cndmask_b32_e32 v46, 0, v216, vcc
	v_sub_f32_e32 v37, v37, v46
	v_lshlrev_b32_e32 v46, 16, v84
	v_mul_f32_e32 v46, 0xbfb8aa3b, v46
	v_exp_f32_e32 v46, v46
	s_nop 0
	v_add_f32_e32 v46, 1.0, v46
	v_rcp_f32_e32 v46, v46
	s_nop 0
	v_pk_fma_f32 v[38:39], v[46:47], v[62:63], v[38:39]
	s_nop 0
	v_cmp_gt_f32_e32 vcc, s63, v38
	s_nop 1
	v_cndmask_b32_e64 v46, 0, 32, vcc
	v_ldexp_f32 v46, v38, v46
	v_log_f32_e32 v46, v46
	s_nop 0
	v_mul_f32_e32 v47, 0x3f317217, v46
	v_fma_f32 v47, v46, s61, -v47
	v_fmac_f32_e32 v47, 0x3377d1cf, v46
	v_fmac_f32_e32 v47, 0x3f317217, v46
	v_cmp_lt_f32_e64 s[10:11], |v46|, s55
	s_nop 1
	v_cndmask_b32_e64 v46, v46, v47, s[10:11]
	v_cndmask_b32_e32 v47, 0, v216, vcc
	v_cmp_gt_f32_e32 vcc, s63, v39
	v_sub_f32_e32 v46, v46, v47
	s_nop 0
	v_cndmask_b32_e64 v47, 0, 32, vcc
	v_ldexp_f32 v47, v39, v47
	v_log_f32_e32 v47, v47
	s_nop 0
	v_mul_f32_e32 v48, 0x3f317217, v47
	v_fma_f32 v48, v47, s61, -v48
	v_fmac_f32_e32 v48, 0x3377d1cf, v47
	v_fmac_f32_e32 v48, 0x3f317217, v47
	v_cmp_lt_f32_e64 s[10:11], |v47|, s55
	s_nop 1
	v_cndmask_b32_e64 v47, v47, v48, s[10:11]
	v_cndmask_b32_e32 v48, 0, v216, vcc
	v_sub_f32_e32 v47, v47, v48
	v_lshlrev_b32_e32 v48, 16, v85
	v_mul_f32_e32 v48, 0xbfb8aa3b, v48
	v_exp_f32_e32 v48, v48
	s_nop 0
	v_add_f32_e32 v48, 1.0, v48
	v_rcp_f32_e32 v48, v48
	s_nop 0
	v_pk_fma_f32 v[40:41], v[48:49], v[64:65], v[40:41]
	s_nop 0
	v_cmp_gt_f32_e32 vcc, s63, v40
	s_nop 1
	v_cndmask_b32_e64 v48, 0, 32, vcc
	v_ldexp_f32 v48, v40, v48
	v_log_f32_e32 v48, v48
	s_nop 0
	v_mul_f32_e32 v49, 0x3f317217, v48
	v_fma_f32 v49, v48, s61, -v49
	v_fmac_f32_e32 v49, 0x3377d1cf, v48
	v_fmac_f32_e32 v49, 0x3f317217, v48
	v_cmp_lt_f32_e64 s[10:11], |v48|, s55
	s_nop 1
	v_cndmask_b32_e64 v48, v48, v49, s[10:11]
	v_cndmask_b32_e32 v49, 0, v216, vcc
	v_cmp_gt_f32_e32 vcc, s63, v41
	v_sub_f32_e32 v48, v48, v49
	s_nop 0
	v_cndmask_b32_e64 v49, 0, 32, vcc
	v_ldexp_f32 v49, v41, v49
	v_log_f32_e32 v49, v49
	s_nop 0
	v_mul_f32_e32 v56, 0x3f317217, v49
	v_fma_f32 v56, v49, s61, -v56
	v_fmac_f32_e32 v56, 0x3377d1cf, v49
	v_fmac_f32_e32 v56, 0x3f317217, v49
	v_cmp_lt_f32_e64 s[10:11], |v49|, s55
	s_nop 1
	v_cndmask_b32_e64 v49, v49, v56, s[10:11]
	v_cndmask_b32_e32 v56, 0, v216, vcc
	v_sub_f32_e32 v49, v49, v56
	ds_write_b128 v170, v[34:37] offset:16384
	ds_write_b128 v170, v[46:49] offset:16400
	s_waitcnt lgkmcnt(0)
	s_barrier
	ds_read2st64_b32 v[34:35], v207 offset0:124 offset1:126
	s_waitcnt lgkmcnt(0)
	v_add_f32_e32 v35, 0, v35
	v_add_f32_e32 v36, v35, v34
	ds_write2st64_b32 v207, v36, v35 offset0:124 offset1:126
	ds_read2st64_b32 v[34:35], v207 offset0:120 offset1:122
	s_waitcnt lgkmcnt(0)
	v_add_f32_e32 v35, v36, v35
	v_add_f32_e32 v36, v35, v34
	ds_write2st64_b32 v207, v36, v35 offset0:120 offset1:122
	ds_read2st64_b32 v[34:35], v207 offset0:116 offset1:118
	s_waitcnt lgkmcnt(0)
	v_add_f32_e32 v35, v36, v35
	v_add_f32_e32 v36, v35, v34
	ds_write2st64_b32 v207, v36, v35 offset0:116 offset1:118
	ds_read2st64_b32 v[34:35], v207 offset0:112 offset1:114
	s_waitcnt lgkmcnt(0)
	v_add_f32_e32 v35, v36, v35
	v_add_f32_e32 v36, v35, v34
	ds_write2st64_b32 v207, v36, v35 offset0:112 offset1:114
	ds_read2st64_b32 v[34:35], v207 offset0:108 offset1:110
	s_waitcnt lgkmcnt(0)
	v_add_f32_e32 v35, v36, v35
	v_add_f32_e32 v36, v35, v34
	ds_write2st64_b32 v207, v36, v35 offset0:108 offset1:110
	ds_read2st64_b32 v[34:35], v207 offset0:104 offset1:106
	s_waitcnt lgkmcnt(0)
	v_add_f32_e32 v35, v36, v35
	v_add_f32_e32 v36, v35, v34
	ds_write2st64_b32 v207, v36, v35 offset0:104 offset1:106
	ds_read2st64_b32 v[34:35], v207 offset0:100 offset1:102
	s_waitcnt lgkmcnt(0)
	v_add_f32_e32 v35, v36, v35
	v_add_f32_e32 v36, v35, v34
	ds_write2st64_b32 v207, v36, v35 offset0:100 offset1:102
	ds_read2st64_b32 v[34:35], v207 offset0:96 offset1:98
	s_waitcnt lgkmcnt(0)
	v_add_f32_e32 v35, v36, v35
	v_add_f32_e32 v34, v35, v34
	ds_write2st64_b32 v207, v34, v35 offset0:96 offset1:98
	ds_write_b32 v159, v34
	s_waitcnt lgkmcnt(0)
	s_barrier
	s_and_saveexec_b64 s[0:1], s[8:9]
	s_cbranch_execz .LBB0_790
	v_mov_b32_e32 v90, 0
	s_mov_b64 s[10:11], 0
	v_mov_b32_e32 v35, v135
	v_mov_b32_e32 v36, v158
